# attention off-diagonal key tiles: S1 MFMAs overlap softmax0 VALU and PV0 MFMAs overlap softmax1 VALU (rare rescale falls back to original path); token-shift mix coefficients staged in LDS so the per-c
# speedup vs baseline: 1.1155x; 1.0169x over previous
; __device__ __forceinline__ int otid() { int t = (int)threadIdx.x; asm volatile("" : "+v"(t)); return t; }
; __device__ __forceinline__ int obid() { int t = (int)blockIdx.x; asm volatile("" : "+s"(t)); return t; }
; template <bool LN>
; __device__ __forceinline__ void ln_phase(const void* src, const float* g, const float* bt, float* xout, h16* xh, const float* mu, h16* mix) {
;     const int lane = otid() & 63, gw = obid() * 8 + (otid() >> 6), GW = gridDim.x * 8;
;     for (int ch = gw; ch < MTOK / 8; ch += GW) {
;         const size_t t0 = (size_t)ch * 8;
;         f32x4 prev[8], cur[8];
;         if (mix) {
;             if ((t0 & (SEQ - 1)) == 0) {
; #pragma unroll
;                 for (int i = 0; i < 8; ++i) prev[i] = (f32x4){0.f, 0.f, 0.f, 0.f};
;             } else ln_row<LN>(src, t0 - 1, lane, g, bt, prev);
;         }
;         h16x4 raw[8], rawn[8];
;         if (LN) ln_load16(src, t0, lane, raw);
.LBB0_114:
	v_mov_b32_e32 v0, v240
	s_mov_b32 s0, s29
	s_waitcnt vmcnt(0)
	v_mov_b32_e32 v2, v240
	s_lshl_b32 s22, s0, 3
	v_ashrrev_i32_e32 v2, 6, v2
	v_add_u32_e32 v70, s22, v2
	v_cmp_gt_i32_e32 vcc, s2, v70
	s_and_saveexec_b64 s[0:1], vcc
	s_movk_i32 s2, 0x7ff
	s_cbranch_execz .LBB0_130
	v_readlane_b32 s3, v255, 9
	v_and_b32_e32 v3, 63, v0
	v_readlane_b32 s4, v254, 54
	v_readlane_b32 s16, v255, 25
	s_lshl_b32 s20, s3, 12
	v_readlane_b32 s3, v255, 12
	v_lshlrev_b32_e32 v0, 4, v3
	v_lshlrev_b32_e32 v12, 3, v3
	v_mov_b32_e32 v13, v1
	v_readlane_b32 s5, v254, 55
	v_readlane_b32 s17, v255, 26
	s_cmp_eq_u32 s3, 9
	v_lshl_add_u64 v[92:93], s[4:5], 0, v[12:13]
	v_lshl_add_u64 v[94:95], s[16:17], 0, v[0:1]
	s_mov_b64 s[4:5], 0x2400
	s_cselect_b32 s21, 0, 0x800
	v_lshl_add_u64 v[106:107], v[94:95], 0, s[4:5]
	s_mov_b64 s[4:5], 0x4400
	s_or_b32 s24, s20, s21
	v_lshl_add_u64 v[108:109], v[94:95], 0, s[4:5]
	s_mov_b64 s[4:5], 0x6400
	s_lshl_b64 s[20:21], s[24:25], 2
	v_lshl_add_u64 v[110:111], v[94:95], 0, s[4:5]
	s_mov_b64 s[4:5], 0x8400
	s_add_u32 s26, s70, s20
	v_lshl_add_u64 v[112:113], v[94:95], 0, s[4:5]
	s_mov_b64 s[4:5], 0xa400
	s_addc_u32 s27, s71, s21
	v_lshl_add_u64 v[114:115], v[94:95], 0, s[4:5]
	s_mov_b64 s[4:5], 0x2800
	s_add_u32 s20, s72, s20
	v_readlane_b32 s10, v255, 23
	v_lshl_add_u64 v[116:117], v[94:95], 0, s[4:5]
	s_mov_b64 s[4:5], 0x4800
	s_addc_u32 s21, s73, s21
	v_readlane_b32 s11, v255, 24
	v_lshl_add_u64 v[118:119], v[94:95], 0, s[4:5]
	s_mov_b64 s[4:5], 0x6800
	s_cmp_lg_u64 s[10:11], 0
	v_lshl_add_u64 v[120:121], v[94:95], 0, s[4:5]
	s_mov_b64 s[4:5], 0x8800
	s_cselect_b64 s[42:43], -1, 0
	s_cmp_lg_u64 s[8:9], 0
	v_lshl_add_u64 v[122:123], v[94:95], 0, s[4:5]
	s_mov_b64 s[4:5], 0xa800
	s_cselect_b64 s[44:45], -1, 0
	s_cmp_lg_u64 s[38:39], 0
	v_lshl_add_u64 v[124:125], v[94:95], 0, s[4:5]
	s_mov_b64 s[4:5], 0x2c00
	s_cselect_b64 s[46:47], -1, 0
	v_lshl_add_u64 v[126:127], v[94:95], 0, s[4:5]
	s_mov_b64 s[4:5], 0x4c00
	v_ashrrev_i32_e32 v3, 31, v2
	s_ashr_i32 s23, s22, 31
	v_or_b32_e32 v4, 0x1000, v0
	v_mov_b32_e32 v5, v1
	v_lshl_add_u64 v[128:129], v[94:95], 0, s[4:5]
	s_mov_b64 s[4:5], 0x6c00
	v_lshl_add_u64 v[2:3], v[2:3], 0, s[22:23]
	v_lshl_add_u64 v[76:77], s[26:27], 0, v[4:5]
	v_lshl_add_u64 v[78:79], s[20:21], 0, v[4:5]
	v_lshl_add_u64 v[130:131], v[94:95], 0, s[4:5]
	s_mov_b64 s[4:5], 0x8c00
	v_lshl_add_u64 v[136:137], s[16:17], 0, v[4:5]
	v_lshlrev_b64 v[4:5], 15, v[2:3]
	v_lshlrev_b64 v[2:3], 16, v[2:3]
	v_or_b32_e32 v6, 0x1400, v0
	v_mov_b32_e32 v7, v1
	v_or_b32_e32 v8, 0x1800, v0
	v_mov_b32_e32 v9, v1
	v_or_b32_e32 v10, 0x1c00, v0
	v_mov_b32_e32 v11, v1
	v_lshl_add_u64 v[132:133], v[94:95], 0, s[4:5]
	s_mov_b64 s[4:5], 0xac00
	v_or_b32_e32 v2, v2, v0
	v_lshl_add_u64 v[72:73], s[26:27], 0, v[0:1]
	v_lshl_add_u64 v[74:75], s[20:21], 0, v[0:1]
	v_lshl_add_u64 v[80:81], s[26:27], 0, v[6:7]
	v_lshl_add_u64 v[82:83], s[20:21], 0, v[6:7]
	v_lshl_add_u64 v[84:85], s[26:27], 0, v[8:9]
	v_lshl_add_u64 v[86:87], s[20:21], 0, v[8:9]
	v_lshl_add_u64 v[88:89], s[26:27], 0, v[10:11]
	v_lshl_add_u64 v[90:91], s[20:21], 0, v[10:11]
	s_mov_b64 s[6:7], 0x4000
	s_mov_b64 s[18:19], 0x6000
	s_mov_b64 s[20:21], 0x8000
	s_mov_b64 s[26:27], 0xa000
	v_lshl_add_u64 v[134:135], v[94:95], 0, s[4:5]
	v_lshl_add_u64 v[148:149], s[16:17], 0, v[6:7]
	v_lshl_add_u64 v[160:161], s[16:17], 0, v[8:9]
	v_lshl_add_u64 v[172:173], s[16:17], 0, v[10:11]
	v_or_b32_e32 v4, v4, v12
	v_lshl_add_u64 v[2:3], s[8:9], 0, v[2:3]
	s_mov_b64 s[4:5], 0x1000
	s_mov_b64 s[40:41], 0
	v_lshl_add_u64 v[96:97], v[94:95], 0, s[90:91]
	v_lshl_add_u64 v[98:99], v[94:95], 0, s[6:7]
	v_lshl_add_u64 v[100:101], v[94:95], 0, s[18:19]
	v_lshl_add_u64 v[102:103], v[94:95], 0, s[20:21]
	v_lshl_add_u64 v[104:105], v[94:95], 0, s[26:27]
	v_lshl_add_u64 v[138:139], v[136:137], 0, s[90:91]
	v_lshl_add_u64 v[140:141], v[136:137], 0, s[6:7]
	v_lshl_add_u64 v[142:143], v[136:137], 0, s[18:19]
	v_lshl_add_u64 v[144:145], v[136:137], 0, s[20:21]
	v_lshl_add_u64 v[146:147], v[136:137], 0, s[26:27]
	v_lshl_add_u64 v[150:151], v[148:149], 0, s[90:91]
	v_lshl_add_u64 v[152:153], v[148:149], 0, s[6:7]
	v_lshl_add_u64 v[154:155], v[148:149], 0, s[18:19]
	v_lshl_add_u64 v[156:157], v[148:149], 0, s[20:21]
	v_lshl_add_u64 v[158:159], v[148:149], 0, s[26:27]
	v_lshl_add_u64 v[162:163], v[160:161], 0, s[90:91]
	v_lshl_add_u64 v[164:165], v[160:161], 0, s[6:7]
	v_lshl_add_u64 v[166:167], v[160:161], 0, s[18:19]
	v_lshl_add_u64 v[168:169], v[160:161], 0, s[20:21]
	v_lshl_add_u64 v[170:171], v[160:161], 0, s[26:27]
	v_lshl_add_u64 v[174:175], v[172:173], 0, s[90:91]
	v_lshl_add_u64 v[176:177], v[172:173], 0, s[6:7]
	v_lshl_add_u64 v[178:179], v[172:173], 0, s[18:19]
	s_mov_b64 s[18:19], 0x90000
	s_mov_b64 s[16:17], 0x80000
	v_lshl_add_u64 v[180:181], v[172:173], 0, s[20:21]
	v_lshl_add_u64 v[182:183], v[172:173], 0, s[26:27]
	v_lshl_add_u64 v[184:185], s[10:11], 0, v[4:5]
	v_lshl_add_u64 v[186:187], v[2:3], 0, s[4:5]
	v_lshl_add_u64 v[188:189], s[38:39], 0, v[4:5]
	v_readfirstlane_b32 s100, v94
	v_readfirstlane_b32 s101, v95
	s_nop 3
	s_cmp_eq_u64 s[100:101], 0
	s_cbranch_scc1 .Lmix_nostage_a
	v_and_b32_e32 v230, 63, v240
	v_lshrrev_b32_e32 v232, 6, v240
	v_lshlrev_b32_e32 v230, 4, v230
	v_readfirstlane_b32 s100, v232
	s_mov_b32 s101, 0
	s_nop 3
	s_mul_i32 s100, s100, 0x1800
	v_lshl_add_u64 v[232:233], v[94:95], 0, s[100:101]
	s_mov_b32 m0, s100
	s_nop 0
	global_load_lds_dwordx4 v[232:233], off
	global_load_lds_dwordx4 v[232:233], off offset:1024
	global_load_lds_dwordx4 v[232:233], off offset:2048
	global_load_lds_dwordx4 v[232:233], off offset:3072
	s_add_i32 s100, s100, 0x1000
	v_lshl_add_u64 v[232:233], v[94:95], 0, s[100:101]
	s_mov_b32 m0, s100
	s_nop 0
	global_load_lds_dwordx4 v[232:233], off
	global_load_lds_dwordx4 v[232:233], off offset:1024
	s_waitcnt vmcnt(0)
	s_barrier
.Lmix_nostage_a:
	s_branch .LBB0_117

; template <bool LN>
; __device__ __forceinline__ void ln_phase(const void* src, const float* g, const float* bt, float* xout, h16* xh, const float* mu, h16* mix) {
;     ...
;             if (mix) {
; #pragma unroll
;                 for (int i = 0; i < 8; ++i) {
;                     asm volatile("" ::: "memory");
;                     const f32x4 xx = prev[i] - cur[i];
; #pragma unroll
;                     for (int k = 0; k < 6; ++k) {
;                         const f32x4 m4 = ((const f32x4*)(mu + (size_t)k * DM))[i * 64 + lane];
;                         const f32x4 o4 = cur[i] + xx * m4;
;                         h16x4 o = {(h16)o4[0], (h16)o4[1], (h16)o4[2], (h16)o4[3]};
;                         ((h16x4*)(mix + ((size_t)k * MTOK + row) * DM))[i * 64 + lane] = o;
;                     }
;                     prev[i] = cur[i];
;                 }
.LBB0_122:
	v_sub_f32_e32 v213, v65, v5
	v_sub_f32_e32 v212, v64, v4
	ds_read_b128 v[64:67], v230 offset:0
	v_sub_f32_e32 v225, v63, v3
	v_sub_f32_e32 v224, v62, v2
	v_lshl_add_u64 v[62:63], v[184:185], 0, s[22:23]
	s_brev_b32 s20, 32
	s_waitcnt lgkmcnt(0)
	v_pk_fma_f32 v[66:67], v[212:213], v[66:67], v[4:5]
	v_pk_fma_f32 v[64:65], v[224:225], v[64:65], v[2:3]
	v_cvt_pk_f16_f32 v67, v66, v67
	v_cvt_pk_f16_f32 v66, v64, v65
	global_store_dwordx2 v[62:63], v[66:67], off
	ds_read_b128 v[64:67], v230 offset:8192
	s_waitcnt lgkmcnt(0)
	v_pk_fma_f32 v[64:65], v[224:225], v[64:65], v[2:3]
	v_pk_fma_f32 v[66:67], v[212:213], v[66:67], v[4:5]
	v_cvt_pk_f16_f32 v68, v64, v65
	v_add_co_u32_e32 v64, vcc, s20, v62
	v_cvt_pk_f16_f32 v69, v66, v67
	s_nop 0
	v_addc_co_u32_e32 v65, vcc, 0, v63, vcc
	global_store_dwordx2 v[64:65], v[68:69], off
	ds_read_b128 v[66:69], v230 offset:16384
	s_brev_b32 s20, 16
	s_waitcnt lgkmcnt(0)
	v_pk_fma_f32 v[66:67], v[224:225], v[66:67], v[2:3]
	v_pk_fma_f32 v[68:69], v[212:213], v[68:69], v[4:5]
	v_cvt_pk_f16_f32 v214, v66, v67
	v_add_co_u32_e32 v66, vcc, s20, v62
	v_cvt_pk_f16_f32 v215, v68, v69
	s_nop 0
	v_addc_co_u32_e32 v67, vcc, 0, v63, vcc
	global_store_dwordx2 v[66:67], v[214:215], off
	ds_read_b128 v[226:229], v230 offset:24576
	s_brev_b32 s20, 48
	s_waitcnt lgkmcnt(0)
	v_pk_fma_f32 v[68:69], v[212:213], v[228:229], v[4:5]
	v_pk_fma_f32 v[214:215], v[224:225], v[226:227], v[2:3]
	s_nop 0
	v_cvt_pk_f16_f32 v214, v214, v215
	v_cvt_pk_f16_f32 v215, v68, v69
	v_add_co_u32_e32 v68, vcc, s20, v62
	s_brev_b32 s20, 8
	s_nop 0
	v_addc_co_u32_e32 v69, vcc, 0, v63, vcc
	global_store_dwordx2 v[68:69], v[214:215], off
	ds_read_b128 v[226:229], v230 offset:32768
	v_add_co_u32_e32 v222, vcc, s20, v62
	s_brev_b32 s20, 40
	s_nop 0
	v_addc_co_u32_e32 v223, vcc, 0, v63, vcc
	s_waitcnt lgkmcnt(0)
	v_pk_fma_f32 v[214:215], v[212:213], v[228:229], v[4:5]
	v_pk_fma_f32 v[216:217], v[224:225], v[226:227], v[2:3]
	s_nop 0
	v_cvt_pk_f16_f32 v216, v216, v217
	v_cvt_pk_f16_f32 v217, v214, v215
	global_store_dwordx2 v[222:223], v[216:217], off
	ds_read_b128 v[226:229], v230 offset:40960
	s_waitcnt lgkmcnt(0)
	v_pk_fma_f32 v[212:213], v[212:213], v[228:229], v[4:5]
	v_pk_fma_f32 v[214:215], v[224:225], v[226:227], v[2:3]
	v_add_co_u32_e32 v224, vcc, s20, v62
	v_cvt_pk_f16_f32 v214, v214, v215
	v_cvt_pk_f16_f32 v215, v212, v213
	v_addc_co_u32_e32 v225, vcc, 0, v63, vcc
	global_store_dwordx2 v[224:225], v[214:215], off
	v_sub_f32_e32 v213, v55, v7
	v_sub_f32_e32 v212, v54, v6
	v_sub_f32_e32 v215, v57, v9
	v_sub_f32_e32 v214, v56, v8
	ds_read_b128 v[54:57], v230 offset:1024
	s_waitcnt lgkmcnt(0)
	v_pk_fma_f32 v[56:57], v[214:215], v[56:57], v[8:9]
	v_pk_fma_f32 v[54:55], v[212:213], v[54:55], v[6:7]
	s_nop 0
	v_cvt_pk_f16_f32 v54, v54, v55
	v_cvt_pk_f16_f32 v55, v56, v57
	global_store_dwordx2 v[62:63], v[54:55], off offset:512
	ds_read_b128 v[54:57], v230 offset:9216
	s_waitcnt lgkmcnt(0)
	v_pk_fma_f32 v[56:57], v[214:215], v[56:57], v[8:9]
	v_pk_fma_f32 v[54:55], v[212:213], v[54:55], v[6:7]
	s_nop 0
	v_cvt_pk_f16_f32 v54, v54, v55
	v_cvt_pk_f16_f32 v55, v56, v57
	global_store_dwordx2 v[64:65], v[54:55], off offset:512
	ds_read_b128 v[54:57], v230 offset:17408
	s_waitcnt lgkmcnt(0)
	v_pk_fma_f32 v[56:57], v[214:215], v[56:57], v[8:9]
	v_pk_fma_f32 v[54:55], v[212:213], v[54:55], v[6:7]
	s_nop 0
	v_cvt_pk_f16_f32 v54, v54, v55
	v_cvt_pk_f16_f32 v55, v56, v57
	global_store_dwordx2 v[66:67], v[54:55], off offset:512
	ds_read_b128 v[54:57], v230 offset:25600
	s_waitcnt lgkmcnt(0)
	v_pk_fma_f32 v[56:57], v[214:215], v[56:57], v[8:9]
	v_pk_fma_f32 v[54:55], v[212:213], v[54:55], v[6:7]
	s_nop 0
	v_cvt_pk_f16_f32 v54, v54, v55
	v_cvt_pk_f16_f32 v55, v56, v57
	global_store_dwordx2 v[68:69], v[54:55], off offset:512
	ds_read_b128 v[54:57], v230 offset:33792
	s_waitcnt lgkmcnt(0)
	v_pk_fma_f32 v[56:57], v[214:215], v[56:57], v[8:9]
	v_pk_fma_f32 v[54:55], v[212:213], v[54:55], v[6:7]
	s_nop 0
	v_cvt_pk_f16_f32 v54, v54, v55
	v_cvt_pk_f16_f32 v55, v56, v57
	global_store_dwordx2 v[222:223], v[54:55], off offset:512
	ds_read_b128 v[54:57], v230 offset:41984
	s_waitcnt lgkmcnt(0)
	v_pk_fma_f32 v[56:57], v[214:215], v[56:57], v[8:9]
	v_pk_fma_f32 v[54:55], v[212:213], v[54:55], v[6:7]
	s_nop 0
	v_cvt_pk_f16_f32 v54, v54, v55
	v_cvt_pk_f16_f32 v55, v56, v57
	global_store_dwordx2 v[224:225], v[54:55], off offset:512
	v_sub_f32_e32 v55, v51, v11
	v_sub_f32_e32 v54, v50, v10
	v_sub_f32_e32 v57, v53, v13
	v_sub_f32_e32 v56, v52, v12
	ds_read_b128 v[50:53], v230 offset:2048
	s_waitcnt lgkmcnt(0)
	v_pk_fma_f32 v[52:53], v[56:57], v[52:53], v[12:13]
	v_pk_fma_f32 v[50:51], v[54:55], v[50:51], v[10:11]
	s_nop 0
	v_cvt_pk_f16_f32 v50, v50, v51
	v_cvt_pk_f16_f32 v51, v52, v53
	global_store_dwordx2 v[62:63], v[50:51], off offset:1024
	ds_read_b128 v[50:53], v230 offset:10240
	s_waitcnt lgkmcnt(0)
	v_pk_fma_f32 v[52:53], v[56:57], v[52:53], v[12:13]
	v_pk_fma_f32 v[50:51], v[54:55], v[50:51], v[10:11]
	s_nop 0
	v_cvt_pk_f16_f32 v50, v50, v51
	v_cvt_pk_f16_f32 v51, v52, v53
	global_store_dwordx2 v[64:65], v[50:51], off offset:1024
	ds_read_b128 v[50:53], v230 offset:18432
	s_waitcnt lgkmcnt(0)
	v_pk_fma_f32 v[52:53], v[56:57], v[52:53], v[12:13]
	v_pk_fma_f32 v[50:51], v[54:55], v[50:51], v[10:11]
	s_nop 0
	v_cvt_pk_f16_f32 v50, v50, v51
	v_cvt_pk_f16_f32 v51, v52, v53
	global_store_dwordx2 v[66:67], v[50:51], off offset:1024
	ds_read_b128 v[50:53], v230 offset:26624
	s_waitcnt lgkmcnt(0)
	v_pk_fma_f32 v[52:53], v[56:57], v[52:53], v[12:13]
	v_pk_fma_f32 v[50:51], v[54:55], v[50:51], v[10:11]
	s_nop 0
	v_cvt_pk_f16_f32 v50, v50, v51
	v_cvt_pk_f16_f32 v51, v52, v53
	global_store_dwordx2 v[68:69], v[50:51], off offset:1024
	ds_read_b128 v[50:53], v230 offset:34816
	s_waitcnt lgkmcnt(0)
; template <bool LN>
; __device__ __forceinline__ void ln_phase(const void* src, const float* g, const float* bt, float* xout, h16* xh, const float* mu, h16* mix) {
;     ...
;             if (mix) {
; #pragma unroll
;                 for (int i = 0; i < 8; ++i) {
;                     asm volatile("" ::: "memory");
;                     const f32x4 xx = prev[i] - cur[i];
; #pragma unroll
;                     for (int k = 0; k < 6; ++k) {
;                         const f32x4 m4 = ((const f32x4*)(mu + (size_t)k * DM))[i * 64 + lane];
;                         const f32x4 o4 = cur[i] + xx * m4;
;                         h16x4 o = {(h16)o4[0], (h16)o4[1], (h16)o4[2], (h16)o4[3]};
;                         ((h16x4*)(mix + ((size_t)k * MTOK + row) * DM))[i * 64 + lane] = o;
;                     }
;                     prev[i] = cur[i];
;                 }
	v_pk_fma_f32 v[52:53], v[56:57], v[52:53], v[12:13]
	v_pk_fma_f32 v[50:51], v[54:55], v[50:51], v[10:11]
	s_nop 0
	v_cvt_pk_f16_f32 v50, v50, v51
	v_cvt_pk_f16_f32 v51, v52, v53
	global_store_dwordx2 v[222:223], v[50:51], off offset:1024
	ds_read_b128 v[50:53], v230 offset:43008
	s_waitcnt lgkmcnt(0)
	v_pk_fma_f32 v[52:53], v[56:57], v[52:53], v[12:13]
	v_pk_fma_f32 v[50:51], v[54:55], v[50:51], v[10:11]
	s_nop 0
	v_cvt_pk_f16_f32 v50, v50, v51
	v_cvt_pk_f16_f32 v51, v52, v53
	global_store_dwordx2 v[224:225], v[50:51], off offset:1024
	v_sub_f32_e32 v51, v47, v15
	v_sub_f32_e32 v50, v46, v14
	v_sub_f32_e32 v53, v49, v17
	v_sub_f32_e32 v52, v48, v16
	ds_read_b128 v[46:49], v230 offset:3072
	s_waitcnt lgkmcnt(0)
	v_pk_fma_f32 v[48:49], v[52:53], v[48:49], v[16:17]
	v_pk_fma_f32 v[46:47], v[50:51], v[46:47], v[14:15]
	s_nop 0
	v_cvt_pk_f16_f32 v46, v46, v47
	v_cvt_pk_f16_f32 v47, v48, v49
	global_store_dwordx2 v[62:63], v[46:47], off offset:1536
	ds_read_b128 v[46:49], v230 offset:11264
	s_waitcnt lgkmcnt(0)
	v_pk_fma_f32 v[48:49], v[52:53], v[48:49], v[16:17]
	v_pk_fma_f32 v[46:47], v[50:51], v[46:47], v[14:15]
	s_nop 0
	v_cvt_pk_f16_f32 v46, v46, v47
	v_cvt_pk_f16_f32 v47, v48, v49
	global_store_dwordx2 v[64:65], v[46:47], off offset:1536
	ds_read_b128 v[46:49], v230 offset:19456
	s_waitcnt lgkmcnt(0)
	v_pk_fma_f32 v[48:49], v[52:53], v[48:49], v[16:17]
	v_pk_fma_f32 v[46:47], v[50:51], v[46:47], v[14:15]
	s_nop 0
	v_cvt_pk_f16_f32 v46, v46, v47
	v_cvt_pk_f16_f32 v47, v48, v49
	global_store_dwordx2 v[66:67], v[46:47], off offset:1536
	ds_read_b128 v[46:49], v230 offset:27648
	s_waitcnt lgkmcnt(0)
	v_pk_fma_f32 v[48:49], v[52:53], v[48:49], v[16:17]
	v_pk_fma_f32 v[46:47], v[50:51], v[46:47], v[14:15]
	s_nop 0
	v_cvt_pk_f16_f32 v46, v46, v47
	v_cvt_pk_f16_f32 v47, v48, v49
	global_store_dwordx2 v[68:69], v[46:47], off offset:1536
	ds_read_b128 v[46:49], v230 offset:35840
	s_waitcnt lgkmcnt(0)
	v_pk_fma_f32 v[48:49], v[52:53], v[48:49], v[16:17]
	v_pk_fma_f32 v[46:47], v[50:51], v[46:47], v[14:15]
	s_nop 0
	v_cvt_pk_f16_f32 v46, v46, v47
	v_cvt_pk_f16_f32 v47, v48, v49
	global_store_dwordx2 v[222:223], v[46:47], off offset:1536
	ds_read_b128 v[46:49], v230 offset:44032
	s_waitcnt lgkmcnt(0)
	v_pk_fma_f32 v[48:49], v[52:53], v[48:49], v[16:17]
	v_pk_fma_f32 v[46:47], v[50:51], v[46:47], v[14:15]
	s_nop 0
	v_cvt_pk_f16_f32 v46, v46, v47
	v_cvt_pk_f16_f32 v47, v48, v49
	global_store_dwordx2 v[224:225], v[46:47], off offset:1536
	v_sub_f32_e32 v47, v43, v23
	v_sub_f32_e32 v46, v42, v22
	v_sub_f32_e32 v49, v45, v25
	v_sub_f32_e32 v48, v44, v24
	ds_read_b128 v[42:45], v230 offset:4096
	s_waitcnt lgkmcnt(0)
	v_pk_fma_f32 v[44:45], v[48:49], v[44:45], v[24:25]
	v_pk_fma_f32 v[42:43], v[46:47], v[42:43], v[22:23]
	s_nop 0
	v_cvt_pk_f16_f32 v42, v42, v43
	v_cvt_pk_f16_f32 v43, v44, v45
	global_store_dwordx2 v[62:63], v[42:43], off offset:2048
	ds_read_b128 v[42:45], v230 offset:12288
	s_waitcnt lgkmcnt(0)
	v_pk_fma_f32 v[44:45], v[48:49], v[44:45], v[24:25]
	v_pk_fma_f32 v[42:43], v[46:47], v[42:43], v[22:23]
	s_nop 0
	v_cvt_pk_f16_f32 v42, v42, v43
	v_cvt_pk_f16_f32 v43, v44, v45
	global_store_dwordx2 v[64:65], v[42:43], off offset:2048
	ds_read_b128 v[42:45], v230 offset:20480
	s_waitcnt lgkmcnt(0)
	v_pk_fma_f32 v[44:45], v[48:49], v[44:45], v[24:25]
	v_pk_fma_f32 v[42:43], v[46:47], v[42:43], v[22:23]
	s_nop 0
	v_cvt_pk_f16_f32 v42, v42, v43
	v_cvt_pk_f16_f32 v43, v44, v45
	global_store_dwordx2 v[66:67], v[42:43], off offset:2048
	ds_read_b128 v[42:45], v230 offset:28672
	s_waitcnt lgkmcnt(0)
	v_pk_fma_f32 v[44:45], v[48:49], v[44:45], v[24:25]
	v_pk_fma_f32 v[42:43], v[46:47], v[42:43], v[22:23]
	s_nop 0
	v_cvt_pk_f16_f32 v42, v42, v43
	v_cvt_pk_f16_f32 v43, v44, v45
	global_store_dwordx2 v[68:69], v[42:43], off offset:2048
	ds_read_b128 v[42:45], v230 offset:36864
	s_waitcnt lgkmcnt(0)
	v_pk_fma_f32 v[44:45], v[48:49], v[44:45], v[24:25]
	v_pk_fma_f32 v[42:43], v[46:47], v[42:43], v[22:23]
	s_nop 0
	v_cvt_pk_f16_f32 v42, v42, v43
	v_cvt_pk_f16_f32 v43, v44, v45
	global_store_dwordx2 v[222:223], v[42:43], off offset:2048
	ds_read_b128 v[42:45], v230 offset:45056
	s_waitcnt lgkmcnt(0)
	v_pk_fma_f32 v[44:45], v[48:49], v[44:45], v[24:25]
	v_pk_fma_f32 v[42:43], v[46:47], v[42:43], v[22:23]
	s_nop 0
	v_cvt_pk_f16_f32 v42, v42, v43
	v_cvt_pk_f16_f32 v43, v44, v45
	global_store_dwordx2 v[224:225], v[42:43], off offset:2048
	v_sub_f32_e32 v43, v39, v31
	v_sub_f32_e32 v42, v38, v30
	v_sub_f32_e32 v45, v41, v33
	v_sub_f32_e32 v44, v40, v32
	ds_read_b128 v[38:41], v230 offset:5120
	s_waitcnt lgkmcnt(0)
	v_pk_fma_f32 v[40:41], v[44:45], v[40:41], v[32:33]
	v_pk_fma_f32 v[38:39], v[42:43], v[38:39], v[30:31]
	s_nop 0
	v_cvt_pk_f16_f32 v38, v38, v39
	v_cvt_pk_f16_f32 v39, v40, v41
	global_store_dwordx2 v[62:63], v[38:39], off offset:2560
	ds_read_b128 v[38:41], v230 offset:13312
	s_waitcnt lgkmcnt(0)
	v_pk_fma_f32 v[40:41], v[44:45], v[40:41], v[32:33]
	v_pk_fma_f32 v[38:39], v[42:43], v[38:39], v[30:31]
	s_nop 0
	v_cvt_pk_f16_f32 v38, v38, v39
	v_cvt_pk_f16_f32 v39, v40, v41
	global_store_dwordx2 v[64:65], v[38:39], off offset:2560
	ds_read_b128 v[38:41], v230 offset:21504
	s_waitcnt lgkmcnt(0)
; template <bool LN>
; __device__ __forceinline__ void ln_phase(const void* src, const float* g, const float* bt, float* xout, h16* xh, const float* mu, h16* mix) {
;     ...
;             if (mix) {
; #pragma unroll
;                 for (int i = 0; i < 8; ++i) {
;                     asm volatile("" ::: "memory");
;                     const f32x4 xx = prev[i] - cur[i];
; #pragma unroll
;                     for (int k = 0; k < 6; ++k) {
;                         const f32x4 m4 = ((const f32x4*)(mu + (size_t)k * DM))[i * 64 + lane];
;                         const f32x4 o4 = cur[i] + xx * m4;
;                         h16x4 o = {(h16)o4[0], (h16)o4[1], (h16)o4[2], (h16)o4[3]};
;                         ((h16x4*)(mix + ((size_t)k * MTOK + row) * DM))[i * 64 + lane] = o;
;                     }
;                     prev[i] = cur[i];
;                 }
	v_pk_fma_f32 v[40:41], v[44:45], v[40:41], v[32:33]
	v_pk_fma_f32 v[38:39], v[42:43], v[38:39], v[30:31]
	s_nop 0
	v_cvt_pk_f16_f32 v38, v38, v39
	v_cvt_pk_f16_f32 v39, v40, v41
	global_store_dwordx2 v[66:67], v[38:39], off offset:2560
	ds_read_b128 v[38:41], v230 offset:29696
	s_waitcnt lgkmcnt(0)
	v_pk_fma_f32 v[40:41], v[44:45], v[40:41], v[32:33]
	v_pk_fma_f32 v[38:39], v[42:43], v[38:39], v[30:31]
	s_nop 0
	v_cvt_pk_f16_f32 v38, v38, v39
	v_cvt_pk_f16_f32 v39, v40, v41
	global_store_dwordx2 v[68:69], v[38:39], off offset:2560
	ds_read_b128 v[38:41], v230 offset:37888
	s_waitcnt lgkmcnt(0)
	v_pk_fma_f32 v[40:41], v[44:45], v[40:41], v[32:33]
	v_pk_fma_f32 v[38:39], v[42:43], v[38:39], v[30:31]
	s_nop 0
	v_cvt_pk_f16_f32 v38, v38, v39
	v_cvt_pk_f16_f32 v39, v40, v41
	global_store_dwordx2 v[222:223], v[38:39], off offset:2560
	ds_read_b128 v[38:41], v230 offset:46080
	s_waitcnt lgkmcnt(0)
	v_pk_fma_f32 v[40:41], v[44:45], v[40:41], v[32:33]
	v_pk_fma_f32 v[38:39], v[42:43], v[38:39], v[30:31]
	s_nop 0
	v_cvt_pk_f16_f32 v38, v38, v39
	v_cvt_pk_f16_f32 v39, v40, v41
	global_store_dwordx2 v[224:225], v[38:39], off offset:2560
	v_sub_f32_e32 v39, v27, v35
	v_sub_f32_e32 v38, v26, v34
	v_sub_f32_e32 v41, v29, v37
	v_sub_f32_e32 v40, v28, v36
	ds_read_b128 v[26:29], v230 offset:6144
	s_waitcnt lgkmcnt(0)
	v_pk_fma_f32 v[28:29], v[40:41], v[28:29], v[36:37]
	v_pk_fma_f32 v[26:27], v[38:39], v[26:27], v[34:35]
	s_nop 0
	v_cvt_pk_f16_f32 v26, v26, v27
	v_cvt_pk_f16_f32 v27, v28, v29
	global_store_dwordx2 v[62:63], v[26:27], off offset:3072
	ds_read_b128 v[26:29], v230 offset:14336
	s_waitcnt lgkmcnt(0)
	v_pk_fma_f32 v[28:29], v[40:41], v[28:29], v[36:37]
	v_pk_fma_f32 v[26:27], v[38:39], v[26:27], v[34:35]
	s_nop 0
	v_cvt_pk_f16_f32 v26, v26, v27
	v_cvt_pk_f16_f32 v27, v28, v29
	global_store_dwordx2 v[64:65], v[26:27], off offset:3072
	ds_read_b128 v[26:29], v230 offset:22528
	s_waitcnt lgkmcnt(0)
	v_pk_fma_f32 v[28:29], v[40:41], v[28:29], v[36:37]
	v_pk_fma_f32 v[26:27], v[38:39], v[26:27], v[34:35]
	s_nop 0
	v_cvt_pk_f16_f32 v26, v26, v27
	v_cvt_pk_f16_f32 v27, v28, v29
	global_store_dwordx2 v[66:67], v[26:27], off offset:3072
	ds_read_b128 v[26:29], v230 offset:30720
	s_waitcnt lgkmcnt(0)
	v_pk_fma_f32 v[28:29], v[40:41], v[28:29], v[36:37]
	v_pk_fma_f32 v[26:27], v[38:39], v[26:27], v[34:35]
	s_nop 0
	v_cvt_pk_f16_f32 v26, v26, v27
	v_cvt_pk_f16_f32 v27, v28, v29
	global_store_dwordx2 v[68:69], v[26:27], off offset:3072
	ds_read_b128 v[26:29], v230 offset:38912
	s_waitcnt lgkmcnt(0)
	v_pk_fma_f32 v[28:29], v[40:41], v[28:29], v[36:37]
	v_pk_fma_f32 v[26:27], v[38:39], v[26:27], v[34:35]
	s_nop 0
	v_cvt_pk_f16_f32 v26, v26, v27
	v_cvt_pk_f16_f32 v27, v28, v29
	global_store_dwordx2 v[222:223], v[26:27], off offset:3072
	ds_read_b128 v[26:29], v230 offset:47104
	s_waitcnt lgkmcnt(0)
	v_pk_fma_f32 v[28:29], v[40:41], v[28:29], v[36:37]
	v_pk_fma_f32 v[26:27], v[38:39], v[26:27], v[34:35]
	s_nop 0
	v_cvt_pk_f16_f32 v26, v26, v27
	v_cvt_pk_f16_f32 v27, v28, v29
	global_store_dwordx2 v[224:225], v[26:27], off offset:3072
	v_sub_f32_e32 v27, v19, v59
	v_sub_f32_e32 v26, v18, v58
	v_sub_f32_e32 v29, v21, v61
	v_sub_f32_e32 v28, v20, v60
	ds_read_b128 v[18:21], v230 offset:7168
	s_waitcnt lgkmcnt(0)
	v_pk_fma_f32 v[20:21], v[28:29], v[20:21], v[60:61]
	v_pk_fma_f32 v[18:19], v[26:27], v[18:19], v[58:59]
	s_nop 0
	v_cvt_pk_f16_f32 v18, v18, v19
	v_cvt_pk_f16_f32 v19, v20, v21
	global_store_dwordx2 v[62:63], v[18:19], off offset:3584
	ds_read_b128 v[18:21], v230 offset:15360
	s_waitcnt lgkmcnt(0)
	v_pk_fma_f32 v[20:21], v[28:29], v[20:21], v[60:61]
	v_pk_fma_f32 v[18:19], v[26:27], v[18:19], v[58:59]
	s_nop 0
	v_cvt_pk_f16_f32 v18, v18, v19
	v_cvt_pk_f16_f32 v19, v20, v21
	global_store_dwordx2 v[64:65], v[18:19], off offset:3584
	ds_read_b128 v[18:21], v230 offset:23552
	s_waitcnt lgkmcnt(0)
	v_pk_fma_f32 v[20:21], v[28:29], v[20:21], v[60:61]
	v_pk_fma_f32 v[18:19], v[26:27], v[18:19], v[58:59]
	s_nop 0
	v_cvt_pk_f16_f32 v18, v18, v19
	v_cvt_pk_f16_f32 v19, v20, v21
	global_store_dwordx2 v[66:67], v[18:19], off offset:3584
	ds_read_b128 v[18:21], v230 offset:31744
	s_waitcnt lgkmcnt(0)
	v_pk_fma_f32 v[20:21], v[28:29], v[20:21], v[60:61]
	v_pk_fma_f32 v[18:19], v[26:27], v[18:19], v[58:59]
	s_nop 0
	v_cvt_pk_f16_f32 v18, v18, v19
	v_cvt_pk_f16_f32 v19, v20, v21
	global_store_dwordx2 v[68:69], v[18:19], off offset:3584
	ds_read_b128 v[18:21], v230 offset:39936
	s_waitcnt lgkmcnt(0)
	v_pk_fma_f32 v[20:21], v[28:29], v[20:21], v[60:61]
	v_pk_fma_f32 v[18:19], v[26:27], v[18:19], v[58:59]
	s_nop 0
	v_cvt_pk_f16_f32 v18, v18, v19
	v_cvt_pk_f16_f32 v19, v20, v21
	global_store_dwordx2 v[222:223], v[18:19], off offset:3584
	ds_read_b128 v[18:21], v230 offset:48128
	s_waitcnt lgkmcnt(0)
	v_pk_fma_f32 v[20:21], v[28:29], v[20:21], v[60:61]
	v_pk_fma_f32 v[18:19], v[26:27], v[18:19], v[58:59]
	s_nop 0
	v_cvt_pk_f16_f32 v18, v18, v19
	v_cvt_pk_f16_f32 v19, v20, v21
	global_store_dwordx2 v[224:225], v[18:19], off offset:3584

; #define LAS __attribute__((address_space(3)))
; __device__ __forceinline__ void attn_phase(LAS unsigned char* lds, const h16* Qb, const h16* Kb, const h16* Vt, h16* AO, const float* rel_bias, const float* lam, const float* subg, float lambda_init) {
;     ...
;             for (int kt = 0; kt < nkt; ++kt) {
;                 LAS unsigned char* cb = lds + (kt & 1) * STG; LAS unsigned char* nb = lds + ((kt & 1) ^ 1) * STG;
;                 const bool near = kt >= 2 * qb - 2;
;                 if (kt + 1 < nkt) ATT_ISSUE(kt + 1, nb);
; #pragma unroll
;                 for (int kb = 0; kb < 2; ++kb) {
;                     if (64 * kt + 32 * kb <= q0 + 32 * rg + 31) {
;                         f32x16 S0;
; #pragma unroll
;                         for (int r = 0; r < 16; ++r) S0[r] = 0.f;
;                         LAS unsigned char* ks = cb + (32 * kb + l32) * 512 + mp * 256;
; #pragma unroll
;                         for (int k = 0; k < 8; ++k) {
;                             const h16x8 a0 = *(LAS h16x8*)(ks + (((2 * k + hh) ^ xk) << 4));
;                             S0 = __builtin_amdgcn_mfma_f32_32x32x16_f16(a0, Qf[k], S0, 0, 0, 0);
;                         }
;                         if (near) {
; #pragma unroll
;                             for (int r = 0; r < 16; ++r) {
;                                 const int kp = 64 * kt + 32 * kb + (r >> 2) * 8 + hh * 4 + (r & 3); const int d0 = qrow - kp;
;                                 const int di = d0 < 0 ? 0 : (d0 > 128 ? 128 : d0); const float bv = lut[di];
;                                 S0[r] = d0 < 0 ? -1e30f : S0[r] + bv;
.LBB0_168:
	s_add_i32 s22, s21, 0
	s_cmp_ge_i32 s20, s35
	s_cselect_b64 s[20:21], -1, 0
	s_add_i32 s23, s22, s81
	v_add_u32_e32 v0, s23, v226
	v_cndmask_b32_e64 v2, 0, 1, s[20:21]
	v_add_u32_e32 v10, s22, v225
	s_cmp_gt_i32 s50, s48
	v_add_u32_e32 v213, v0, v227
	v_add_u32_e32 v212, v0, v228
	v_add_u32_e32 v245, v0, v229
	v_add_u32_e32 v15, v0, v230
	v_add_u32_e32 v14, v0, v231
	v_add_u32_e32 v13, v0, v232
	v_add_u32_e32 v12, v0, v233
	v_add_u32_e32 v11, v0, v234
	v_cmp_ne_u32_e64 s[38:39], 1, v2
	s_mov_b64 vcc, s[20:21]
	s_cbranch_vccz .Lattn_fast
	s_cbranch_scc1 .LBB0_206
	ds_read_b128 v[160:163], v213
	ds_read_b128 v[164:167], v212
	ds_read_b128 v[168:171], v245
	ds_read_b128 v[172:175], v15
	s_and_b64 vcc, exec, s[38:39]
	s_waitcnt lgkmcnt(3)
	v_mfma_f32_32x32x16_f16 v[144:159], v[160:163], v[176:179], 0
	ds_read_b128 v[160:163], v14
	s_waitcnt lgkmcnt(3)
	v_mfma_f32_32x32x16_f16 v[144:159], v[164:167], v[180:183], v[144:159]
	ds_read_b128 v[164:167], v13
	s_waitcnt lgkmcnt(3)
	v_mfma_f32_32x32x16_f16 v[144:159], v[168:171], v[184:187], v[144:159]
	ds_read_b128 v[168:171], v12
	s_waitcnt lgkmcnt(3)
	v_mfma_f32_32x32x16_f16 v[144:159], v[172:175], v[188:191], v[144:159]
	ds_read_b128 v[172:175], v11
	s_waitcnt lgkmcnt(3)
	v_mfma_f32_32x32x16_f16 v[144:159], v[160:163], v[192:195], v[144:159]
	s_waitcnt lgkmcnt(2)
	v_mfma_f32_32x32x16_f16 v[144:159], v[164:167], v[196:199], v[144:159]
	s_waitcnt lgkmcnt(1)
	v_mfma_f32_32x32x16_f16 v[144:159], v[168:171], v[200:203], v[144:159]
	s_waitcnt lgkmcnt(0)
	v_mfma_f32_32x32x16_f16 v[144:159], v[172:175], v[204:207], v[144:159]
	s_cbranch_vccnz .LBB0_203
	v_add_u32_e32 v0, 27, v239
	v_cmp_lt_i32_e32 vcc, -1, v0
	v_mov_b32_e32 v161, 0xf149f2ca
	v_mov_b32_e32 v160, 0xf149f2ca
	s_and_saveexec_b64 s[22:23], vcc
	s_cbranch_execz .LBB0_172
	v_min_u32_e32 v0, 0x80, v0
	v_lshl_add_u32 v0, v0, 2, 0
	v_add_u32_e32 v0, 0x20000, v0
	ds_read_b32 v0, v0
	s_waitcnt lgkmcnt(0)
	v_add_f32_e32 v160, v144, v0

; #define LAS __attribute__((address_space(3)))
; __device__ __forceinline__ void attn_phase(LAS unsigned char* lds, const h16* Qb, const h16* Kb, const h16* Vt, h16* AO, const float* rel_bias, const float* lam, const float* subg, float lambda_init) {
;     ...
; #pragma unroll
;                 for (int kb = 0; kb < 2; ++kb) {
;                     if (64 * kt + 32 * kb <= q0 + 32 * rg + 31) {
;                         f32x16 S0;
; #pragma unroll
;                         for (int r = 0; r < 16; ++r) S0[r] = 0.f;
;                         LAS unsigned char* ks = cb + (32 * kb + l32) * 512 + mp * 256;
; #pragma unroll
;                         for (int k = 0; k < 8; ++k) {
;                             const h16x8 a0 = *(LAS h16x8*)(ks + (((2 * k + hh) ^ xk) << 4));
;                             S0 = __builtin_amdgcn_mfma_f32_32x32x16_f16(a0, Qf[k], S0, 0, 0, 0);
;                         }
;                         if (near) {
; #pragma unroll
;                             for (int r = 0; r < 16; ++r) {
;                                 const int kp = 64 * kt + 32 * kb + (r >> 2) * 8 + hh * 4 + (r & 3); const int d0 = qrow - kp;
;                                 const int di = d0 < 0 ? 0 : (d0 > 128 ? 128 : d0); const float bv = lut[di];
;                                 S0[r] = d0 < 0 ? -1e30f : S0[r] + bv;
;                             }
;                         }
;                         float mt = S0[0];
; #pragma unroll
;                         for (int r = 1; r < 16; ++r) mt = fmaxf(mt, S0[r]);
;                         if (__builtin_amdgcn_ballot_w64(mt - mrun > 10.0f) != 0ull) {
;                             const float mo = fmaxf(mt, __shfl_xor(mt, 32));
;                             const float mn = fmaxf(mrun, mo);
;                             const float al = __builtin_amdgcn_exp2f(mrun - mn);
;                             mrun = mn; lrun *= al;
; #pragma unroll
;                             for (int i = 0; i < 8; ++i) O[i] = O[i] * al;
;                         }
;                         float ps = 0.f;
; #pragma unroll
;                         for (int r = 0; r < 16; ++r) { S0[r] = __builtin_amdgcn_exp2f(S0[r] - mrun); ps += S0[r]; }
;                         lrun += ps;
;                         h16x8 P0, P1;
; #pragma unroll
;                         for (int e = 0; e < 8; ++e) { P0[e] = (h16)S0[e]; P1[e] = (h16)S0[8 + e]; }
.Lattn_fast:
	ds_read_b128 v[2:5], v213
	ds_read_b128 v[6:9], v212
	ds_read_b128 v[214:217], v245
	s_waitcnt lgkmcnt(2)
	v_mfma_f32_32x32x16_f16 v[144:159], v[2:5], v[176:179], 0
	ds_read_b128 v[2:5], v15
	s_waitcnt lgkmcnt(2)
	v_mfma_f32_32x32x16_f16 v[144:159], v[6:9], v[180:183], v[144:159]
	ds_read_b128 v[6:9], v14
	s_waitcnt lgkmcnt(2)
	v_mfma_f32_32x32x16_f16 v[144:159], v[214:217], v[184:187], v[144:159]
	ds_read_b128 v[214:217], v13
	s_waitcnt lgkmcnt(2)
	v_mfma_f32_32x32x16_f16 v[144:159], v[2:5], v[188:191], v[144:159]
	ds_read_b128 v[2:5], v12
	s_waitcnt lgkmcnt(2)
	v_mfma_f32_32x32x16_f16 v[144:159], v[6:9], v[192:195], v[144:159]
	ds_read_b128 v[6:9], v11
	s_waitcnt lgkmcnt(2)
	v_mfma_f32_32x32x16_f16 v[144:159], v[214:217], v[196:199], v[144:159]
	s_waitcnt lgkmcnt(1)
	v_mfma_f32_32x32x16_f16 v[144:159], v[2:5], v[200:203], v[144:159]
	s_waitcnt lgkmcnt(0)
	v_mfma_f32_32x32x16_f16 v[144:159], v[6:9], v[204:207], v[144:159]
	ds_read_b128 v[2:5], v213 offset:16384
	ds_read_b128 v[214:217], v212 offset:16384
	s_waitcnt lgkmcnt(1)
	v_mfma_f32_32x32x16_f16 v[160:175], v[2:5], v[176:179], 0
	ds_read_b128 v[2:5], v245 offset:16384
	s_waitcnt lgkmcnt(1)
	v_mfma_f32_32x32x16_f16 v[160:175], v[214:217], v[180:183], v[160:175]
	ds_read_b128 v[214:217], v15 offset:16384
	s_nop 3
	v_max_f32_e32 v0, v145, v145
	v_max_f32_e32 v6, v144, v144
	v_max_f32_e32 v0, v6, v0
	v_max3_f32 v0, v0, v146, v147
	v_max3_f32 v0, v0, v148, v149
	v_max3_f32 v0, v0, v150, v151
	v_max3_f32 v0, v0, v152, v153
	v_max3_f32 v0, v0, v154, v155
	v_max3_f32 v0, v0, v156, v157
	v_max3_f32 v0, v0, v158, v159
	v_sub_f32_e32 v6, v0, v250
	v_cmp_lt_f32_e32 vcc, s58, v6
	s_cbranch_vccnz .Lattn_rare0
	v_sub_f32_e32 v144, v144, v250
	v_exp_f32_e32 v144, v144
	v_sub_f32_e32 v145, v145, v250
	v_exp_f32_e32 v145, v145
	v_add_f32_e32 v0, 0, v144
	v_sub_f32_e32 v146, v146, v250
	v_exp_f32_e32 v146, v146
	s_waitcnt lgkmcnt(1)
	v_mfma_f32_32x32x16_f16 v[160:175], v[2:5], v[184:187], v[160:175]
	ds_read_b128 v[2:5], v14 offset:16384
	v_add_f32_e32 v0, v145, v0
	v_sub_f32_e32 v147, v147, v250
	v_exp_f32_e32 v147, v147
	v_add_f32_e32 v0, v146, v0
	v_sub_f32_e32 v148, v148, v250
	v_exp_f32_e32 v148, v148
	v_add_f32_e32 v0, v147, v0
	v_sub_f32_e32 v149, v149, v250
	s_waitcnt lgkmcnt(1)
	v_mfma_f32_32x32x16_f16 v[160:175], v[214:217], v[188:191], v[160:175]
	ds_read_b128 v[214:217], v13 offset:16384
	v_exp_f32_e32 v149, v149
	v_add_f32_e32 v0, v148, v0
	v_sub_f32_e32 v150, v150, v250
	v_exp_f32_e32 v150, v150
	v_add_f32_e32 v0, v149, v0
	v_sub_f32_e32 v151, v151, v250
	v_exp_f32_e32 v151, v151
	v_add_f32_e32 v0, v150, v0
	s_waitcnt lgkmcnt(1)
	v_mfma_f32_32x32x16_f16 v[160:175], v[2:5], v[192:195], v[160:175]
	ds_read_b128 v[2:5], v12 offset:16384
	v_sub_f32_e32 v152, v152, v250
	v_exp_f32_e32 v152, v152
	v_add_f32_e32 v0, v151, v0
	v_sub_f32_e32 v153, v153, v250
	v_exp_f32_e32 v153, v153
	v_add_f32_e32 v0, v152, v0
	v_sub_f32_e32 v154, v154, v250
	v_exp_f32_e32 v154, v154
	s_waitcnt lgkmcnt(1)
	v_mfma_f32_32x32x16_f16 v[160:175], v[214:217], v[196:199], v[160:175]
	ds_read_b128 v[214:217], v11 offset:16384
	v_add_f32_e32 v0, v153, v0
	v_sub_f32_e32 v155, v155, v250
	v_exp_f32_e32 v155, v155
	v_add_f32_e32 v0, v154, v0
	v_sub_f32_e32 v156, v156, v250
	v_exp_f32_e32 v156, v156
	v_add_f32_e32 v0, v155, v0
	v_sub_f32_e32 v157, v157, v250
	s_waitcnt lgkmcnt(1)
	v_mfma_f32_32x32x16_f16 v[160:175], v[2:5], v[200:203], v[160:175]
	v_exp_f32_e32 v157, v157
	v_add_f32_e32 v0, v156, v0
	v_sub_f32_e32 v158, v158, v250
	v_exp_f32_e32 v158, v158
	v_add_f32_e32 v0, v157, v0
	v_sub_f32_e32 v159, v159, v250
	v_exp_f32_e32 v159, v159
	v_add_f32_e32 v0, v158, v0
	s_waitcnt lgkmcnt(0)
	v_mfma_f32_32x32x16_f16 v[160:175], v[214:217], v[204:207], v[160:175]
	v_cvt_pk_f16_f32 v6, v144, v145
	v_cvt_pk_f16_f32 v7, v146, v147
	v_cvt_pk_f16_f32 v8, v148, v149
	v_cvt_pk_f16_f32 v9, v150, v151
	v_add_f32_e32 v0, v159, v0
	v_add_f32_e32 v224, v224, v0
	v_cvt_pk_f16_f32 v12, v152, v153
	v_cvt_pk_f16_f32 v13, v154, v155
	v_cvt_pk_f16_f32 v14, v156, v157
	v_cvt_pk_f16_f32 v15, v158, v159
	v_add_u32_e32 v11, v10, v235
	v_add_u32_e32 v213, v10, v236
	v_add_u32_e32 v212, v10, v237
	v_add_u32_e32 v245, v10, v238
	ds_read_b128 v[144:147], v11 offset:32768
	ds_read_b128 v[148:151], v11 offset:36864
	ds_read_b128 v[152:155], v11 offset:40960
	ds_read_b128 v[156:159], v11 offset:45056
	v_max_f32_e32 v0, v161, v161
	v_max_f32_e32 v2, v160, v160
	v_max_f32_e32 v0, v2, v0
	v_max3_f32 v0, v0, v162, v163
	v_max3_f32 v0, v0, v164, v165
	v_max3_f32 v0, v0, v166, v167
	v_max3_f32 v0, v0, v168, v169
	v_max3_f32 v0, v0, v170, v171
	v_max3_f32 v0, v0, v172, v173
	v_max3_f32 v0, v0, v174, v175
	v_sub_f32_e32 v2, v0, v250
	v_cmp_lt_f32_e32 vcc, s58, v2
	s_cbranch_vccnz .Lattn_rare1
; #define LAS __attribute__((address_space(3)))
; __device__ __forceinline__ void attn_phase(LAS unsigned char* lds, const h16* Qb, const h16* Kb, const h16* Vt, h16* AO, const float* rel_bias, const float* lam, const float* subg, float lambda_init) {
;     ...
;                         float ps = 0.f;
; #pragma unroll
;                         for (int r = 0; r < 16; ++r) { S0[r] = __builtin_amdgcn_exp2f(S0[r] - mrun); ps += S0[r]; }
;                         lrun += ps;
;                         h16x8 P0, P1;
; #pragma unroll
;                         for (int e = 0; e < 8; ++e) { P0[e] = (h16)S0[e]; P1[e] = (h16)S0[8 + e]; }
;                         LAS unsigned char* vs = cb + 32768 + l32 * 128;
;                         const int vo0 = ((4 * kb + hh) ^ yv) << 4, vo1 = ((4 * kb + 2 + hh) ^ yv) << 4;
; #pragma unroll
;                         for (int dvb = 0; dvb < 8; ++dvb) {
;                             const h16x8 a = *(LAS h16x8*)(vs + dvb * 4096 + vo0);
;                             O[dvb] = __builtin_amdgcn_mfma_f32_32x32x16_f16(a, P0, O[dvb], 0, 0, 0);
;                         }
; #pragma unroll
;                         for (int dvb = 0; dvb < 8; ++dvb) {
;                             const h16x8 a = *(LAS h16x8*)(vs + dvb * 4096 + vo1);
;                             O[dvb] = __builtin_amdgcn_mfma_f32_32x32x16_f16(a, P1, O[dvb], 0, 0, 0);
;                         }
	v_sub_f32_e32 v160, v160, v250
	v_exp_f32_e32 v160, v160
	v_sub_f32_e32 v161, v161, v250
	v_exp_f32_e32 v161, v161
	s_waitcnt lgkmcnt(3)
	v_mfma_f32_32x32x16_f16 v[128:143], v[144:147], v[6:9], v[128:143]
	ds_read_b128 v[144:147], v11 offset:49152
	v_add_f32_e32 v0, 0, v160
	v_sub_f32_e32 v162, v162, v250
	v_exp_f32_e32 v162, v162
	v_add_f32_e32 v0, v161, v0
	s_waitcnt lgkmcnt(3)
	v_mfma_f32_32x32x16_f16 v[112:127], v[148:151], v[6:9], v[112:127]
	ds_read_b128 v[148:151], v11 offset:53248
	v_sub_f32_e32 v163, v163, v250
	v_exp_f32_e32 v163, v163
	v_add_f32_e32 v0, v162, v0
	v_sub_f32_e32 v164, v164, v250
	s_waitcnt lgkmcnt(3)
	v_mfma_f32_32x32x16_f16 v[96:111], v[152:155], v[6:9], v[96:111]
	ds_read_b128 v[152:155], v11 offset:57344
	v_exp_f32_e32 v164, v164
	v_add_f32_e32 v0, v163, v0
	v_sub_f32_e32 v165, v165, v250
	v_exp_f32_e32 v165, v165
	s_waitcnt lgkmcnt(3)
	v_mfma_f32_32x32x16_f16 v[80:95], v[156:159], v[6:9], v[80:95]
	ds_read_b128 v[156:159], v11 offset:61440
	v_add_f32_e32 v0, v164, v0
	v_sub_f32_e32 v166, v166, v250
	v_exp_f32_e32 v166, v166
	v_add_f32_e32 v0, v165, v0
	s_waitcnt lgkmcnt(3)
	v_mfma_f32_32x32x16_f16 v[64:79], v[144:147], v[6:9], v[64:79]
	ds_read_b128 v[144:147], v213 offset:32768
	v_sub_f32_e32 v167, v167, v250
	v_exp_f32_e32 v167, v167
	v_add_f32_e32 v0, v166, v0
	v_sub_f32_e32 v168, v168, v250
	s_waitcnt lgkmcnt(3)
	v_mfma_f32_32x32x16_f16 v[48:63], v[148:151], v[6:9], v[48:63]
	ds_read_b128 v[148:151], v213 offset:36864
	v_exp_f32_e32 v168, v168
	v_add_f32_e32 v0, v167, v0
	v_sub_f32_e32 v169, v169, v250
	v_exp_f32_e32 v169, v169
	s_waitcnt lgkmcnt(3)
	v_mfma_f32_32x32x16_f16 v[32:47], v[152:155], v[6:9], v[32:47]
	ds_read_b128 v[152:155], v213 offset:40960
	v_add_f32_e32 v0, v168, v0
	v_sub_f32_e32 v170, v170, v250
	v_exp_f32_e32 v170, v170
	v_add_f32_e32 v0, v169, v0
	s_waitcnt lgkmcnt(3)
	v_mfma_f32_32x32x16_f16 v[16:31], v[156:159], v[6:9], v[16:31]
	ds_read_b128 v[156:159], v213 offset:45056
	v_sub_f32_e32 v171, v171, v250
	v_exp_f32_e32 v171, v171
	v_add_f32_e32 v0, v170, v0
	v_sub_f32_e32 v172, v172, v250
	s_waitcnt lgkmcnt(3)
	v_mfma_f32_32x32x16_f16 v[128:143], v[144:147], v[12:15], v[128:143]
	ds_read_b128 v[144:147], v213 offset:49152
	v_exp_f32_e32 v172, v172
	v_add_f32_e32 v0, v171, v0
	v_sub_f32_e32 v173, v173, v250
	v_exp_f32_e32 v173, v173
	s_waitcnt lgkmcnt(3)
	v_mfma_f32_32x32x16_f16 v[112:127], v[148:151], v[12:15], v[112:127]
	ds_read_b128 v[148:151], v213 offset:53248
	v_add_f32_e32 v0, v172, v0
	v_sub_f32_e32 v174, v174, v250
	v_exp_f32_e32 v174, v174
	v_add_f32_e32 v0, v173, v0
	s_waitcnt lgkmcnt(3)
	v_mfma_f32_32x32x16_f16 v[96:111], v[152:155], v[12:15], v[96:111]
	ds_read_b128 v[152:155], v213 offset:57344
	v_sub_f32_e32 v175, v175, v250
	v_exp_f32_e32 v175, v175
	v_add_f32_e32 v0, v174, v0
	v_cvt_pk_f16_f32 v2, v160, v161
	s_waitcnt lgkmcnt(3)
	v_mfma_f32_32x32x16_f16 v[80:95], v[156:159], v[12:15], v[80:95]
	ds_read_b128 v[156:159], v213 offset:61440
	v_cvt_pk_f16_f32 v3, v162, v163
	v_cvt_pk_f16_f32 v4, v164, v165
	v_cvt_pk_f16_f32 v5, v166, v167
	v_add_f32_e32 v0, v175, v0
	s_waitcnt lgkmcnt(3)
	v_mfma_f32_32x32x16_f16 v[64:79], v[144:147], v[12:15], v[64:79]
	ds_read_b128 v[144:147], v212 offset:32768
	v_add_f32_e32 v224, v224, v0
	v_cvt_pk_f16_f32 v214, v168, v169
	v_cvt_pk_f16_f32 v215, v170, v171
	v_cvt_pk_f16_f32 v216, v172, v173
	s_waitcnt lgkmcnt(3)
	v_mfma_f32_32x32x16_f16 v[48:63], v[148:151], v[12:15], v[48:63]
	ds_read_b128 v[148:151], v212 offset:36864
	v_cvt_pk_f16_f32 v217, v174, v175
	s_waitcnt lgkmcnt(3)
	v_mfma_f32_32x32x16_f16 v[32:47], v[152:155], v[12:15], v[32:47]
	ds_read_b128 v[152:155], v212 offset:40960
	s_waitcnt lgkmcnt(3)
	v_mfma_f32_32x32x16_f16 v[16:31], v[156:159], v[12:15], v[16:31]
	ds_read_b128 v[156:159], v212 offset:45056
	s_nop 0
	s_waitcnt lgkmcnt(3)
	v_mfma_f32_32x32x16_f16 v[128:143], v[144:147], v[2:5], v[128:143]
	ds_read_b128 v[144:147], v212 offset:49152
	s_waitcnt lgkmcnt(3)
	v_mfma_f32_32x32x16_f16 v[112:127], v[148:151], v[2:5], v[112:127]
	ds_read_b128 v[148:151], v212 offset:53248
	s_waitcnt lgkmcnt(3)
	v_mfma_f32_32x32x16_f16 v[96:111], v[152:155], v[2:5], v[96:111]
	ds_read_b128 v[152:155], v212 offset:57344
	s_waitcnt lgkmcnt(3)
	v_mfma_f32_32x32x16_f16 v[80:95], v[156:159], v[2:5], v[80:95]
	ds_read_b128 v[156:159], v212 offset:61440
	s_waitcnt lgkmcnt(3)
	v_mfma_f32_32x32x16_f16 v[64:79], v[144:147], v[2:5], v[64:79]
	ds_read_b128 v[144:147], v245 offset:32768
	s_waitcnt lgkmcnt(3)
	v_mfma_f32_32x32x16_f16 v[48:63], v[148:151], v[2:5], v[48:63]
	ds_read_b128 v[148:151], v245 offset:36864
	s_waitcnt lgkmcnt(3)
	v_mfma_f32_32x32x16_f16 v[32:47], v[152:155], v[2:5], v[32:47]
	ds_read_b128 v[152:155], v245 offset:40960
	s_waitcnt lgkmcnt(3)
	v_mfma_f32_32x32x16_f16 v[16:31], v[156:159], v[2:5], v[16:31]
	ds_read_b128 v[156:159], v245 offset:45056
	s_waitcnt lgkmcnt(3)
	v_mfma_f32_32x32x16_f16 v[128:143], v[144:147], v[214:217], v[128:143]
	ds_read_b128 v[144:147], v245 offset:49152
	s_waitcnt lgkmcnt(3)
	v_mfma_f32_32x32x16_f16 v[112:127], v[148:151], v[214:217], v[112:127]
	ds_read_b128 v[148:151], v245 offset:53248
	s_waitcnt lgkmcnt(3)
	v_mfma_f32_32x32x16_f16 v[96:111], v[152:155], v[214:217], v[96:111]
	ds_read_b128 v[152:155], v245 offset:57344
	s_waitcnt lgkmcnt(3)
	v_mfma_f32_32x32x16_f16 v[80:95], v[156:159], v[214:217], v[80:95]
	ds_read_b128 v[156:159], v245 offset:61440
	s_waitcnt lgkmcnt(3)
	v_mfma_f32_32x32x16_f16 v[64:79], v[144:147], v[214:217], v[64:79]
	s_waitcnt lgkmcnt(2)
	v_mfma_f32_32x32x16_f16 v[48:63], v[148:151], v[214:217], v[48:63]
	s_waitcnt lgkmcnt(1)
	v_mfma_f32_32x32x16_f16 v[32:47], v[152:155], v[214:217], v[32:47]
	s_waitcnt lgkmcnt(0)
	v_mfma_f32_32x32x16_f16 v[16:31], v[156:159], v[214:217], v[16:31]
	s_branch .LBB0_244
; #define LAS __attribute__((address_space(3)))
; __device__ __forceinline__ void attn_phase(LAS unsigned char* lds, const h16* Qb, const h16* Kb, const h16* Vt, h16* AO, const float* rel_bias, const float* lam, const float* subg, float lambda_init) {
;     ...
;                         if (__builtin_amdgcn_ballot_w64(mt - mrun > 10.0f) != 0ull) {
;                             const float mo = fmaxf(mt, __shfl_xor(mt, 32));
;                             const float mn = fmaxf(mrun, mo);
;                             const float al = __builtin_amdgcn_exp2f(mrun - mn);
;                             mrun = mn; lrun *= al;
; #pragma unroll
;                             for (int i = 0; i < 8; ++i) O[i] = O[i] * al;
;                         }
;                         float ps = 0.f;
; #pragma unroll
;                         for (int r = 0; r < 16; ++r) { S0[r] = __builtin_amdgcn_exp2f(S0[r] - mrun); ps += S0[r]; }
;                         lrun += ps;
;                         h16x8 P0, P1;
; #pragma unroll
;                         for (int e = 0; e < 8; ++e) { P0[e] = (h16)S0[e]; P1[e] = (h16)S0[8 + e]; }
;                         LAS unsigned char* vs = cb + 32768 + l32 * 128;
;                         const int vo0 = ((4 * kb + hh) ^ yv) << 4, vo1 = ((4 * kb + 2 + hh) ^ yv) << 4;
; #pragma unroll
;                         for (int dvb = 0; dvb < 8; ++dvb) {
;                             const h16x8 a = *(LAS h16x8*)(vs + dvb * 4096 + vo0);
;                             O[dvb] = __builtin_amdgcn_mfma_f32_32x32x16_f16(a, P0, O[dvb], 0, 0, 0);
;                         }
; #pragma unroll
;                         for (int dvb = 0; dvb < 8; ++dvb) {
;                             const h16x8 a = *(LAS h16x8*)(vs + dvb * 4096 + vo1);
;                             O[dvb] = __builtin_amdgcn_mfma_f32_32x32x16_f16(a, P1, O[dvb], 0, 0, 0);
;                         }
.Lattn_rare0:
	s_waitcnt lgkmcnt(0)
	s_branch .LBB0_203
.Lattn_rare1:
	s_waitcnt lgkmcnt(3)
	v_mfma_f32_32x32x16_f16 v[128:143], v[144:147], v[6:9], v[128:143]
	ds_read_b128 v[144:147], v11 offset:49152
	s_waitcnt lgkmcnt(3)
	v_mfma_f32_32x32x16_f16 v[112:127], v[148:151], v[6:9], v[112:127]
	ds_read_b128 v[148:151], v11 offset:53248
	s_waitcnt lgkmcnt(3)
	v_mfma_f32_32x32x16_f16 v[96:111], v[152:155], v[6:9], v[96:111]
	ds_read_b128 v[152:155], v11 offset:57344
	s_waitcnt lgkmcnt(3)
	v_mfma_f32_32x32x16_f16 v[80:95], v[156:159], v[6:9], v[80:95]
	ds_read_b128 v[156:159], v11 offset:61440
	s_waitcnt lgkmcnt(3)
	v_mfma_f32_32x32x16_f16 v[64:79], v[144:147], v[6:9], v[64:79]
	ds_read_b128 v[144:147], v213 offset:32768
	s_waitcnt lgkmcnt(3)
	v_mfma_f32_32x32x16_f16 v[48:63], v[148:151], v[6:9], v[48:63]
	ds_read_b128 v[148:151], v213 offset:36864
	s_waitcnt lgkmcnt(3)
	v_mfma_f32_32x32x16_f16 v[32:47], v[152:155], v[6:9], v[32:47]
	ds_read_b128 v[152:155], v213 offset:40960
	s_waitcnt lgkmcnt(3)
	v_mfma_f32_32x32x16_f16 v[16:31], v[156:159], v[6:9], v[16:31]
	ds_read_b128 v[156:159], v213 offset:45056
	s_waitcnt lgkmcnt(3)
	v_mfma_f32_32x32x16_f16 v[128:143], v[144:147], v[12:15], v[128:143]
	ds_read_b128 v[144:147], v213 offset:49152
	s_waitcnt lgkmcnt(3)
	v_mfma_f32_32x32x16_f16 v[112:127], v[148:151], v[12:15], v[112:127]
	ds_read_b128 v[148:151], v213 offset:53248
	s_waitcnt lgkmcnt(3)
	v_mfma_f32_32x32x16_f16 v[96:111], v[152:155], v[12:15], v[96:111]
	ds_read_b128 v[152:155], v213 offset:57344
	s_waitcnt lgkmcnt(3)
	v_mfma_f32_32x32x16_f16 v[80:95], v[156:159], v[12:15], v[80:95]
	ds_read_b128 v[156:159], v213 offset:61440
	s_waitcnt lgkmcnt(3)
	v_mfma_f32_32x32x16_f16 v[64:79], v[144:147], v[12:15], v[64:79]
	s_waitcnt lgkmcnt(2)
	v_mfma_f32_32x32x16_f16 v[48:63], v[148:151], v[12:15], v[48:63]
	s_waitcnt lgkmcnt(1)
	v_mfma_f32_32x32x16_f16 v[32:47], v[152:155], v[12:15], v[32:47]
	s_waitcnt lgkmcnt(0)
	v_mfma_f32_32x32x16_f16 v[16:31], v[156:159], v[12:15], v[16:31]
	s_waitcnt lgkmcnt(0)
	v_mov_b64_e32 v[144:145], v[160:161]
	v_mov_b64_e32 v[146:147], v[162:163]
	v_mov_b64_e32 v[148:149], v[164:165]
	v_mov_b64_e32 v[150:151], v[166:167]
	v_mov_b64_e32 v[152:153], v[168:169]
	v_mov_b64_e32 v[154:155], v[170:171]
	v_mov_b64_e32 v[156:157], v[172:173]
	v_mov_b64_e32 v[158:159], v[174:175]
	s_branch .LBB0_241

; __device__ __forceinline__ int otid() { int t = (int)threadIdx.x; asm volatile("" : "+v"(t)); return t; }
; __device__ __forceinline__ int obid() { int t = (int)blockIdx.x; asm volatile("" : "+s"(t)); return t; }
; template <bool LN>
; __device__ __forceinline__ void ln_phase(const void* src, const float* g, const float* bt, float* xout, h16* xh, const float* mu, h16* mix) {
;     const int lane = otid() & 63, gw = obid() * 8 + (otid() >> 6), GW = gridDim.x * 8;
;     for (int ch = gw; ch < MTOK / 8; ch += GW) {
;         const size_t t0 = (size_t)ch * 8;
;         f32x4 prev[8], cur[8];
;         if (mix) {
;             if ((t0 & (SEQ - 1)) == 0) {
; #pragma unroll
;                 for (int i = 0; i < 8; ++i) prev[i] = (f32x4){0.f, 0.f, 0.f, 0.f};
;             } else ln_row<LN>(src, t0 - 1, lane, g, bt, prev);
;         }
;         h16x4 raw[8], rawn[8];
;         if (LN) ln_load16(src, t0, lane, raw);
.LBB0_1008:
	v_mov_b32_e32 v0, v240
	s_mov_b32 s0, s29
	s_waitcnt vmcnt(0)
	v_mov_b32_e32 v2, v240
	s_lshl_b32 s22, s0, 3
	v_ashrrev_i32_e32 v2, 6, v2
	v_add_u32_e32 v68, s22, v2
	v_cmp_gt_i32_e32 vcc, s2, v68
	s_and_saveexec_b64 s[0:1], vcc
	s_movk_i32 s2, 0x7ff
	s_cbranch_execz .LBB0_1015
	v_and_b32_e32 v4, 63, v0
	v_lshlrev_b32_e32 v0, 4, v4
	v_lshl_add_u64 v[70:71], s[74:75], 0, v[0:1]
	s_mov_b64 s[4:5], 0x2400
	v_lshl_add_u64 v[82:83], v[70:71], 0, s[4:5]
	s_mov_b64 s[4:5], 0x4400
	v_lshl_add_u64 v[84:85], v[70:71], 0, s[4:5]
	s_mov_b64 s[4:5], 0x6400
	v_lshl_add_u64 v[86:87], v[70:71], 0, s[4:5]
	s_mov_b64 s[4:5], 0x8400
	v_lshl_add_u64 v[88:89], v[70:71], 0, s[4:5]
	s_mov_b64 s[4:5], 0xa400
	v_lshl_add_u64 v[90:91], v[70:71], 0, s[4:5]
	s_mov_b64 s[4:5], 0x2800
	v_lshl_add_u64 v[92:93], v[70:71], 0, s[4:5]
	s_mov_b64 s[4:5], 0x4800
	v_lshl_add_u64 v[94:95], v[70:71], 0, s[4:5]
	s_mov_b64 s[4:5], 0x6800
	v_lshl_add_u64 v[96:97], v[70:71], 0, s[4:5]
	s_mov_b64 s[4:5], 0x8800
	v_or_b32_e32 v6, 0x1000, v0
	v_mov_b32_e32 v7, v1
	v_lshl_add_u64 v[98:99], v[70:71], 0, s[4:5]
	s_mov_b64 s[4:5], 0xa800
	v_lshl_add_u64 v[108:109], s[74:75], 0, v[6:7]
	v_or_b32_e32 v6, 0x1400, v0
	v_lshl_add_u64 v[100:101], v[70:71], 0, s[4:5]
	s_mov_b64 s[4:5], 0x2c00
	v_lshl_add_u64 v[110:111], s[74:75], 0, v[6:7]
	v_or_b32_e32 v6, 0x1800, v0
	v_lshl_add_u64 v[102:103], v[70:71], 0, s[4:5]
	s_mov_b64 s[4:5], 0x4c00
	v_lshl_add_u64 v[112:113], s[74:75], 0, v[6:7]
	v_or_b32_e32 v6, 0x1c00, v0
	v_ashrrev_i32_e32 v3, 31, v2
	s_ashr_i32 s23, s22, 31
	v_lshl_add_u64 v[104:105], v[70:71], 0, s[4:5]
	s_mov_b64 s[4:5], 0x6c00
	v_lshl_add_u64 v[114:115], s[74:75], 0, v[6:7]
	v_lshlrev_b64 v[6:7], 15, v[2:3]
	v_lshl_add_u64 v[2:3], v[2:3], 0, s[22:23]
	v_lshl_add_u64 v[106:107], v[70:71], 0, s[4:5]
	v_lshlrev_b64 v[2:3], 16, v[2:3]
	v_readlane_b32 s4, v254, 9
	s_lshl_b64 s[20:21], s[22:23], 15
	v_or_b32_e32 v2, v2, v0
	v_readlane_b32 s5, v254, 10
	v_lshl_add_u64 v[6:7], v[6:7], 0, s[20:21]
	s_mov_b64 s[6:7], 0x4000
	v_lshl_add_u64 v[118:119], s[4:5], 0, v[2:3]
	s_mov_b64 s[4:5], 0x8c00
	s_mov_b64 s[18:19], 0x6000
	s_mov_b64 s[26:27], 0x8000
	s_mov_b64 s[38:39], 0xa000
	v_lshl_or_b32 v6, v4, 3, v6
	v_lshl_add_u64 v[122:123], v[70:71], 0, s[4:5]
	s_mov_b64 s[4:5], 0xac00
	v_lshl_add_u64 v[72:73], v[70:71], 0, s[90:91]
	v_lshl_add_u64 v[74:75], v[70:71], 0, s[6:7]
	v_lshl_add_u64 v[76:77], v[70:71], 0, s[18:19]
	v_lshl_add_u64 v[78:79], v[70:71], 0, s[26:27]
	v_lshl_add_u64 v[80:81], v[70:71], 0, s[38:39]
	v_lshl_add_u64 v[116:117], s[84:85], 0, v[6:7]
	s_mov_b64 s[22:23], 0
	v_lshlrev_b32_e32 v120, 4, v4
	v_lshl_add_u64 v[124:125], v[70:71], 0, s[4:5]
	v_lshl_add_u64 v[126:127], v[108:109], 0, s[90:91]
	v_lshl_add_u64 v[128:129], v[108:109], 0, s[6:7]
	v_lshl_add_u64 v[130:131], v[108:109], 0, s[18:19]
	v_lshl_add_u64 v[132:133], v[108:109], 0, s[26:27]
	v_lshl_add_u64 v[134:135], v[108:109], 0, s[38:39]
	v_lshl_add_u64 v[136:137], v[110:111], 0, s[90:91]
	v_lshl_add_u64 v[138:139], v[110:111], 0, s[6:7]
	v_lshl_add_u64 v[140:141], v[110:111], 0, s[18:19]
	v_lshl_add_u64 v[142:143], v[110:111], 0, s[26:27]
	v_lshl_add_u64 v[144:145], v[110:111], 0, s[38:39]
	v_lshl_add_u64 v[146:147], v[112:113], 0, s[90:91]
	v_lshl_add_u64 v[148:149], v[112:113], 0, s[6:7]
	v_lshl_add_u64 v[150:151], v[112:113], 0, s[18:19]
	v_lshl_add_u64 v[152:153], v[112:113], 0, s[26:27]
	v_lshl_add_u64 v[154:155], v[112:113], 0, s[38:39]
	v_lshl_add_u64 v[156:157], v[114:115], 0, s[90:91]
	v_lshl_add_u64 v[158:159], v[114:115], 0, s[6:7]
	v_lshl_add_u64 v[160:161], v[114:115], 0, s[18:19]
	s_mov_b64 s[18:19], 0x90000
	s_mov_b64 s[16:17], 0x80000
	v_lshl_add_u64 v[162:163], v[114:115], 0, s[26:27]
	v_lshl_add_u64 v[164:165], v[114:115], 0, s[38:39]
	v_readfirstlane_b32 s100, v70
	v_readfirstlane_b32 s101, v71
	s_nop 3
	s_cmp_eq_u64 s[100:101], 0
	s_cbranch_scc1 .Lmix_nostage_b
	v_and_b32_e32 v230, 63, v240
	v_lshrrev_b32_e32 v232, 6, v240
	v_lshlrev_b32_e32 v230, 4, v230
	v_readfirstlane_b32 s100, v232
	s_mov_b32 s101, 0
	s_nop 3
	s_mul_i32 s100, s100, 0x1800
	v_lshl_add_u64 v[232:233], v[70:71], 0, s[100:101]
	s_mov_b32 m0, s100
	s_nop 0
	global_load_lds_dwordx4 v[232:233], off
	global_load_lds_dwordx4 v[232:233], off offset:1024
	global_load_lds_dwordx4 v[232:233], off offset:2048
	global_load_lds_dwordx4 v[232:233], off offset:3072
	s_add_i32 s100, s100, 0x1000
	v_lshl_add_u64 v[232:233], v[70:71], 0, s[100:101]
	s_mov_b32 m0, s100
	s_nop 0
	global_load_lds_dwordx4 v[232:233], off
	global_load_lds_dwordx4 v[232:233], off offset:1024
	s_waitcnt vmcnt(0)
	s_barrier
.Lmix_nostage_b:
.LBB0_1010:
	v_and_b32_e32 v0, 0x3ff, v68
	v_mov_b32_e32 v2, v1
	v_mov_b32_e32 v3, v1
	v_cmp_ne_u32_e32 vcc, 0, v0
	v_mov_b32_e32 v0, v1
	v_mov_b64_e32 v[6:7], v[2:3]
	v_mov_b64_e32 v[42:43], v[2:3]
	v_mov_b64_e32 v[46:47], v[2:3]
	v_mov_b64_e32 v[50:51], v[2:3]
	v_mov_b64_e32 v[54:55], v[2:3]
	v_mov_b64_e32 v[58:59], v[2:3]
	v_mov_b64_e32 v[62:63], v[2:3]
	v_mov_b64_e32 v[66:67], v[2:3]
	v_ashrrev_i32_e32 v69, 31, v68
	v_mov_b64_e32 v[4:5], v[0:1]
	v_mov_b64_e32 v[40:41], v[0:1]
	v_mov_b64_e32 v[44:45], v[0:1]
	v_mov_b64_e32 v[48:49], v[0:1]
	v_mov_b64_e32 v[52:53], v[0:1]
	v_mov_b64_e32 v[56:57], v[0:1]
	v_mov_b64_e32 v[60:61], v[0:1]
	v_mov_b64_e32 v[64:65], v[0:1]
	s_and_saveexec_b64 s[26:27], vcc
	s_cbranch_execz .LBB0_1012
	v_lshlrev_b64 v[2:3], 16, v[68:69]
	v_lshl_add_u64 v[2:3], s[68:69], 0, v[2:3]
	v_mov_b32_e32 v121, v1
	v_lshl_add_u64 v[2:3], v[2:3], 0, v[120:121]
	s_movk_i32 s20, 0xe000
	s_mov_b32 s21, -1
	v_add_co_u32_e32 v6, vcc, 0xffffe000, v2
	v_lshl_add_u64 v[4:5], v[2:3], 0, s[20:21]
	s_nop 0
	v_addc_co_u32_e32 v7, vcc, -1, v3, vcc
	global_load_dwordx4 v[60:63], v[4:5], off offset:1024
	global_load_dwordx4 v[56:59], v[4:5], off offset:2048
	global_load_dwordx4 v[64:67], v[6:7], off
	global_load_dwordx4 v[52:55], v[4:5], off offset:3072
	global_load_dwordx4 v[48:51], v[2:3], off offset:-4096
	global_load_dwordx4 v[44:47], v[2:3], off offset:-3072
	global_load_dwordx4 v[40:43], v[2:3], off offset:-2048
	s_nop 0
	global_load_dwordx4 v[4:7], v[2:3], off offset:-1024

; template <bool LN>
; __device__ __forceinline__ void ln_phase(const void* src, const float* g, const float* bt, float* xout, h16* xh, const float* mu, h16* mix) {
;     ...
;             } else ln_row<LN>(src, row, lane, g, bt, cur);
;             if (xout) {
; #pragma unroll
;                 for (int i = 0; i < 8; ++i) ((f32x4*)(xout + row * DM))[i * 64 + lane] = cur[i];
;             }
;             if (xh) {
; #pragma unroll
;                 for (int i = 0; i < 8; ++i) { h16x4 o = {(h16)cur[i][0], (h16)cur[i][1], (h16)cur[i][2], (h16)cur[i][3]}; ((h16x4*)(xh + row * DM))[i * 64 + lane] = o; }
;             }
;             if (mix) {
; #pragma unroll
;                 for (int i = 0; i < 8; ++i) {
;                     asm volatile("" ::: "memory");
;                     const f32x4 xx = prev[i] - cur[i];
; #pragma unroll
;                     for (int k = 0; k < 6; ++k) {
;                         const f32x4 m4 = ((const f32x4*)(mu + (size_t)k * DM))[i * 64 + lane];
;                         const f32x4 o4 = cur[i] + xx * m4;
;                         h16x4 o = {(h16)o4[0], (h16)o4[1], (h16)o4[2], (h16)o4[3]};
;                         ((h16x4*)(mix + ((size_t)k * MTOK + row) * DM))[i * 64 + lane] = o;
;                     }
;                     prev[i] = cur[i];
;                 }
.LBB0_1013:
	global_load_dwordx4 v[8:11], v[2:3], off offset:-4096
	global_load_dwordx4 v[12:15], v[2:3], off offset:-3072
	global_load_dwordx4 v[16:19], v[2:3], off offset:-2048
	global_load_dwordx4 v[24:27], v[2:3], off offset:-1024
	global_load_dwordx4 v[28:31], v[2:3], off
	global_load_dwordx4 v[32:35], v[2:3], off offset:1024
	global_load_dwordx4 v[36:39], v[2:3], off offset:2048
	global_load_dwordx4 v[20:23], v[2:3], off offset:3072
	v_lshl_add_u64 v[170:171], v[116:117], 0, s[26:27]
	s_mov_b32 s20, 0x17000000
	s_add_u32 s26, s26, 0x1000
	s_addc_u32 s27, s27, 0
	v_lshl_add_u64 v[2:3], v[2:3], 0, s[90:91]
	s_cmpk_eq_u32 s26, 0x8000
	s_waitcnt vmcnt(0)
	v_sub_f32_e32 v174, v64, v8
	v_add_co_u32_e32 v64, vcc, s20, v170
	v_sub_f32_e32 v175, v65, v9
	v_sub_f32_e32 v177, v67, v11
	v_sub_f32_e32 v176, v66, v10
	v_addc_co_u32_e32 v65, vcc, 0, v171, vcc
	v_cvt_pk_f16_f32 v67, v10, v11
	v_cvt_pk_f16_f32 v66, v8, v9
	global_store_dwordx2 v[64:65], v[66:67], off
	v_cvt_pk_f16_f32 v67, v14, v15
	v_cvt_pk_f16_f32 v66, v12, v13
	global_store_dwordx2 v[64:65], v[66:67], off offset:512
	v_cvt_pk_f16_f32 v67, v18, v19
	v_cvt_pk_f16_f32 v66, v16, v17
	global_store_dwordx2 v[64:65], v[66:67], off offset:1024
	v_cvt_pk_f16_f32 v67, v26, v27
	v_cvt_pk_f16_f32 v66, v24, v25
	global_store_dwordx2 v[64:65], v[66:67], off offset:1536
	v_cvt_pk_f16_f32 v67, v30, v31
	v_cvt_pk_f16_f32 v66, v28, v29
	global_store_dwordx2 v[64:65], v[66:67], off offset:2048
	v_cvt_pk_f16_f32 v67, v34, v35
	v_cvt_pk_f16_f32 v66, v32, v33
	global_store_dwordx2 v[64:65], v[66:67], off offset:2560
	v_cvt_pk_f16_f32 v67, v38, v39
	v_cvt_pk_f16_f32 v66, v36, v37
	global_store_dwordx2 v[64:65], v[66:67], off offset:3072
	v_cvt_pk_f16_f32 v67, v22, v23
	v_cvt_pk_f16_f32 v66, v20, v21
	global_store_dwordx2 v[64:65], v[66:67], off offset:3584
	ds_read_b128 v[64:67], v230 offset:0
	s_mov_b32 s20, 0x1f000000
	v_sub_f32_e32 v61, v61, v13
	v_sub_f32_e32 v60, v60, v12
	v_sub_f32_e32 v63, v63, v15
	v_sub_f32_e32 v62, v62, v14
	v_sub_f32_e32 v57, v57, v17
	v_sub_f32_e32 v56, v56, v16
	v_sub_f32_e32 v59, v59, v19
	v_sub_f32_e32 v58, v58, v18
	v_sub_f32_e32 v53, v53, v25
	v_sub_f32_e32 v52, v52, v24
	v_sub_f32_e32 v55, v55, v27
	v_sub_f32_e32 v54, v54, v26
	s_waitcnt lgkmcnt(0)
	v_pk_fma_f32 v[64:65], v[174:175], v[64:65], v[8:9]
	v_pk_fma_f32 v[166:167], v[176:177], v[66:67], v[10:11]
	v_cvt_pk_f16_f32 v66, v64, v65
	v_add_co_u32_e32 v64, vcc, s20, v170
	v_cvt_pk_f16_f32 v67, v166, v167
	s_nop 0
	v_addc_co_u32_e32 v65, vcc, 0, v171, vcc
	global_store_dwordx2 v[64:65], v[66:67], off
	ds_read_b128 v[166:169], v230 offset:8192
	s_mov_b32 s20, 0x23000000
	s_waitcnt lgkmcnt(0)
	v_pk_fma_f32 v[66:67], v[176:177], v[168:169], v[10:11]
	v_pk_fma_f32 v[166:167], v[174:175], v[166:167], v[8:9]
	s_nop 0
	v_cvt_pk_f16_f32 v166, v166, v167
	v_cvt_pk_f16_f32 v167, v66, v67
	v_add_co_u32_e32 v66, vcc, s20, v170
	s_mov_b32 s20, 0x27000000
	s_nop 0
	v_addc_co_u32_e32 v67, vcc, 0, v171, vcc
	global_store_dwordx2 v[66:67], v[166:167], off
	ds_read_b128 v[166:169], v230 offset:16384
	s_waitcnt lgkmcnt(0)
	v_pk_fma_f32 v[166:167], v[174:175], v[166:167], v[8:9]
	v_pk_fma_f32 v[168:169], v[176:177], v[168:169], v[10:11]
	v_cvt_pk_f16_f32 v172, v166, v167
	v_add_co_u32_e32 v166, vcc, s20, v170
	v_cvt_pk_f16_f32 v173, v168, v169
	s_nop 0
	v_addc_co_u32_e32 v167, vcc, 0, v171, vcc
	global_store_dwordx2 v[166:167], v[172:173], off
	ds_read_b128 v[178:181], v230 offset:24576
	s_mov_b32 s20, 0x2b000000
	s_waitcnt lgkmcnt(0)
	v_pk_fma_f32 v[168:169], v[176:177], v[180:181], v[10:11]
	v_pk_fma_f32 v[172:173], v[174:175], v[178:179], v[8:9]
	s_nop 0
	v_cvt_pk_f16_f32 v172, v172, v173
	v_cvt_pk_f16_f32 v173, v168, v169
	v_add_co_u32_e32 v168, vcc, s20, v170
	s_mov_b32 s20, 0x2f000000
	s_nop 0
	v_addc_co_u32_e32 v169, vcc, 0, v171, vcc
	global_store_dwordx2 v[168:169], v[172:173], off
	ds_read_b128 v[178:181], v230 offset:32768
	s_waitcnt lgkmcnt(0)
	v_pk_fma_f32 v[172:173], v[176:177], v[180:181], v[10:11]
	v_pk_fma_f32 v[178:179], v[174:175], v[178:179], v[8:9]
	s_nop 0
	v_cvt_pk_f16_f32 v178, v178, v179
	v_cvt_pk_f16_f32 v179, v172, v173
	v_add_co_u32_e32 v172, vcc, s20, v170
	s_nop 1
	v_addc_co_u32_e32 v173, vcc, 0, v171, vcc
	global_store_dwordx2 v[172:173], v[178:179], off
	ds_read_b128 v[178:181], v230 offset:40960
	v_add_co_u32_e32 v170, vcc, s40, v170
	s_waitcnt lgkmcnt(0)
	v_pk_fma_f32 v[176:177], v[176:177], v[180:181], v[10:11]
	v_pk_fma_f32 v[174:175], v[174:175], v[178:179], v[8:9]
	v_addc_co_u32_e32 v171, vcc, 0, v171, vcc
	v_cvt_pk_f16_f32 v174, v174, v175
	v_cvt_pk_f16_f32 v175, v176, v177
	global_store_dwordx2 v[170:171], v[174:175], off
	ds_read_b128 v[174:177], v230 offset:1024
	s_waitcnt lgkmcnt(0)
	v_pk_fma_f32 v[176:177], v[62:63], v[176:177], v[14:15]
	v_pk_fma_f32 v[174:175], v[60:61], v[174:175], v[12:13]
	s_nop 0
	v_cvt_pk_f16_f32 v174, v174, v175
	v_cvt_pk_f16_f32 v175, v176, v177
	global_store_dwordx2 v[64:65], v[174:175], off offset:512
	ds_read_b128 v[174:177], v230 offset:9216
	s_waitcnt lgkmcnt(0)
	v_pk_fma_f32 v[176:177], v[62:63], v[176:177], v[14:15]
	v_pk_fma_f32 v[174:175], v[60:61], v[174:175], v[12:13]
	s_nop 0
	v_cvt_pk_f16_f32 v174, v174, v175
	v_cvt_pk_f16_f32 v175, v176, v177
	global_store_dwordx2 v[66:67], v[174:175], off offset:512
	ds_read_b128 v[174:177], v230 offset:17408
	s_waitcnt lgkmcnt(0)
	v_pk_fma_f32 v[176:177], v[62:63], v[176:177], v[14:15]
	v_pk_fma_f32 v[174:175], v[60:61], v[174:175], v[12:13]
	s_nop 0
	v_cvt_pk_f16_f32 v174, v174, v175
	v_cvt_pk_f16_f32 v175, v176, v177
	global_store_dwordx2 v[166:167], v[174:175], off offset:512
	ds_read_b128 v[174:177], v230 offset:25600
	s_waitcnt lgkmcnt(0)
; template <bool LN>
; __device__ __forceinline__ void ln_phase(const void* src, const float* g, const float* bt, float* xout, h16* xh, const float* mu, h16* mix) {
;     ...
;             if (mix) {
; #pragma unroll
;                 for (int i = 0; i < 8; ++i) {
;                     asm volatile("" ::: "memory");
;                     const f32x4 xx = prev[i] - cur[i];
; #pragma unroll
;                     for (int k = 0; k < 6; ++k) {
;                         const f32x4 m4 = ((const f32x4*)(mu + (size_t)k * DM))[i * 64 + lane];
;                         const f32x4 o4 = cur[i] + xx * m4;
;                         h16x4 o = {(h16)o4[0], (h16)o4[1], (h16)o4[2], (h16)o4[3]};
;                         ((h16x4*)(mix + ((size_t)k * MTOK + row) * DM))[i * 64 + lane] = o;
;                     }
;                     prev[i] = cur[i];
;                 }
	v_pk_fma_f32 v[176:177], v[62:63], v[176:177], v[14:15]
	v_pk_fma_f32 v[174:175], v[60:61], v[174:175], v[12:13]
	s_nop 0
	v_cvt_pk_f16_f32 v174, v174, v175
	v_cvt_pk_f16_f32 v175, v176, v177
	global_store_dwordx2 v[168:169], v[174:175], off offset:512
	ds_read_b128 v[174:177], v230 offset:33792
	s_waitcnt lgkmcnt(0)
	v_pk_fma_f32 v[176:177], v[62:63], v[176:177], v[14:15]
	v_pk_fma_f32 v[174:175], v[60:61], v[174:175], v[12:13]
	s_nop 0
	v_cvt_pk_f16_f32 v174, v174, v175
	v_cvt_pk_f16_f32 v175, v176, v177
	global_store_dwordx2 v[172:173], v[174:175], off offset:512
	ds_read_b128 v[174:177], v230 offset:41984
	s_waitcnt lgkmcnt(0)
	v_pk_fma_f32 v[62:63], v[62:63], v[176:177], v[14:15]
	v_pk_fma_f32 v[60:61], v[60:61], v[174:175], v[12:13]
	v_sub_f32_e32 v175, v5, v21
	v_cvt_pk_f16_f32 v60, v60, v61
	v_cvt_pk_f16_f32 v61, v62, v63
	global_store_dwordx2 v[170:171], v[60:61], off offset:512
	ds_read_b128 v[60:63], v230 offset:2048
	v_sub_f32_e32 v174, v4, v20
	v_sub_f32_e32 v177, v7, v23
	v_sub_f32_e32 v176, v6, v22
	s_waitcnt lgkmcnt(0)
	v_pk_fma_f32 v[62:63], v[58:59], v[62:63], v[18:19]
	v_pk_fma_f32 v[60:61], v[56:57], v[60:61], v[16:17]
	s_nop 0
	v_cvt_pk_f16_f32 v60, v60, v61
	v_cvt_pk_f16_f32 v61, v62, v63
	global_store_dwordx2 v[64:65], v[60:61], off offset:1024
	ds_read_b128 v[60:63], v230 offset:10240
	s_waitcnt lgkmcnt(0)
	v_pk_fma_f32 v[62:63], v[58:59], v[62:63], v[18:19]
	v_pk_fma_f32 v[60:61], v[56:57], v[60:61], v[16:17]
	s_nop 0
	v_cvt_pk_f16_f32 v60, v60, v61
	v_cvt_pk_f16_f32 v61, v62, v63
	global_store_dwordx2 v[66:67], v[60:61], off offset:1024
	ds_read_b128 v[60:63], v230 offset:18432
	s_waitcnt lgkmcnt(0)
	v_pk_fma_f32 v[62:63], v[58:59], v[62:63], v[18:19]
	v_pk_fma_f32 v[60:61], v[56:57], v[60:61], v[16:17]
	s_nop 0
	v_cvt_pk_f16_f32 v60, v60, v61
	v_cvt_pk_f16_f32 v61, v62, v63
	global_store_dwordx2 v[166:167], v[60:61], off offset:1024
	ds_read_b128 v[60:63], v230 offset:26624
	s_waitcnt lgkmcnt(0)
	v_pk_fma_f32 v[62:63], v[58:59], v[62:63], v[18:19]
	v_pk_fma_f32 v[60:61], v[56:57], v[60:61], v[16:17]
	s_nop 0
	v_cvt_pk_f16_f32 v60, v60, v61
	v_cvt_pk_f16_f32 v61, v62, v63
	global_store_dwordx2 v[168:169], v[60:61], off offset:1024
	ds_read_b128 v[60:63], v230 offset:34816
	s_waitcnt lgkmcnt(0)
	v_pk_fma_f32 v[62:63], v[58:59], v[62:63], v[18:19]
	v_pk_fma_f32 v[60:61], v[56:57], v[60:61], v[16:17]
	s_nop 0
	v_cvt_pk_f16_f32 v60, v60, v61
	v_cvt_pk_f16_f32 v61, v62, v63
	global_store_dwordx2 v[172:173], v[60:61], off offset:1024
	ds_read_b128 v[60:63], v230 offset:43008
	s_waitcnt lgkmcnt(0)
	v_pk_fma_f32 v[58:59], v[58:59], v[62:63], v[18:19]
	v_pk_fma_f32 v[56:57], v[56:57], v[60:61], v[16:17]
	v_mov_b64_e32 v[62:63], v[14:15]
	v_cvt_pk_f16_f32 v56, v56, v57
	v_cvt_pk_f16_f32 v57, v58, v59
	global_store_dwordx2 v[170:171], v[56:57], off offset:1024
	ds_read_b128 v[56:59], v230 offset:3072
	v_mov_b64_e32 v[60:61], v[12:13]
	s_waitcnt lgkmcnt(0)
	v_pk_fma_f32 v[58:59], v[54:55], v[58:59], v[26:27]
	v_pk_fma_f32 v[56:57], v[52:53], v[56:57], v[24:25]
	s_nop 0
	v_cvt_pk_f16_f32 v56, v56, v57
	v_cvt_pk_f16_f32 v57, v58, v59
	global_store_dwordx2 v[64:65], v[56:57], off offset:1536
	ds_read_b128 v[56:59], v230 offset:11264
	s_waitcnt lgkmcnt(0)
	v_pk_fma_f32 v[58:59], v[54:55], v[58:59], v[26:27]
	v_pk_fma_f32 v[56:57], v[52:53], v[56:57], v[24:25]
	s_nop 0
	v_cvt_pk_f16_f32 v56, v56, v57
	v_cvt_pk_f16_f32 v57, v58, v59
	global_store_dwordx2 v[66:67], v[56:57], off offset:1536
	ds_read_b128 v[56:59], v230 offset:19456
	s_waitcnt lgkmcnt(0)
	v_pk_fma_f32 v[58:59], v[54:55], v[58:59], v[26:27]
	v_pk_fma_f32 v[56:57], v[52:53], v[56:57], v[24:25]
	s_nop 0
	v_cvt_pk_f16_f32 v56, v56, v57
	v_cvt_pk_f16_f32 v57, v58, v59
	global_store_dwordx2 v[166:167], v[56:57], off offset:1536
	ds_read_b128 v[56:59], v230 offset:27648
	s_waitcnt lgkmcnt(0)
	v_pk_fma_f32 v[58:59], v[54:55], v[58:59], v[26:27]
	v_pk_fma_f32 v[56:57], v[52:53], v[56:57], v[24:25]
	s_nop 0
	v_cvt_pk_f16_f32 v56, v56, v57
	v_cvt_pk_f16_f32 v57, v58, v59
	global_store_dwordx2 v[168:169], v[56:57], off offset:1536
	ds_read_b128 v[56:59], v230 offset:35840
	s_waitcnt lgkmcnt(0)
	v_pk_fma_f32 v[58:59], v[54:55], v[58:59], v[26:27]
	v_pk_fma_f32 v[56:57], v[52:53], v[56:57], v[24:25]
	s_nop 0
	v_cvt_pk_f16_f32 v56, v56, v57
	v_cvt_pk_f16_f32 v57, v58, v59
	global_store_dwordx2 v[172:173], v[56:57], off offset:1536
	ds_read_b128 v[56:59], v230 offset:44032
	s_waitcnt lgkmcnt(0)
	v_pk_fma_f32 v[54:55], v[54:55], v[58:59], v[26:27]
	v_pk_fma_f32 v[52:53], v[52:53], v[56:57], v[24:25]
	v_sub_f32_e32 v57, v49, v29
	v_cvt_pk_f16_f32 v52, v52, v53
	v_cvt_pk_f16_f32 v53, v54, v55
	global_store_dwordx2 v[170:171], v[52:53], off offset:1536
	ds_read_b128 v[52:55], v230 offset:4096
	v_sub_f32_e32 v56, v48, v28
	v_sub_f32_e32 v59, v51, v31
	v_sub_f32_e32 v58, v50, v30
	s_waitcnt lgkmcnt(0)
	v_pk_fma_f32 v[48:49], v[58:59], v[54:55], v[30:31]
	v_pk_fma_f32 v[50:51], v[56:57], v[52:53], v[28:29]
	v_sub_f32_e32 v53, v45, v33
	v_cvt_pk_f16_f32 v50, v50, v51
	v_cvt_pk_f16_f32 v51, v48, v49
	global_store_dwordx2 v[64:65], v[50:51], off offset:2048
	ds_read_b128 v[48:51], v230 offset:12288
	v_sub_f32_e32 v52, v44, v32
	v_sub_f32_e32 v55, v47, v35
	v_sub_f32_e32 v54, v46, v34
	s_waitcnt lgkmcnt(0)
	v_pk_fma_f32 v[50:51], v[58:59], v[50:51], v[30:31]
	v_pk_fma_f32 v[48:49], v[56:57], v[48:49], v[28:29]
	s_nop 0
	v_cvt_pk_f16_f32 v48, v48, v49
	v_cvt_pk_f16_f32 v49, v50, v51
	global_store_dwordx2 v[66:67], v[48:49], off offset:2048
	ds_read_b128 v[48:51], v230 offset:20480
	s_waitcnt lgkmcnt(0)
; template <bool LN>
; __device__ __forceinline__ void ln_phase(const void* src, const float* g, const float* bt, float* xout, h16* xh, const float* mu, h16* mix) {
;     ...
;             if (mix) {
; #pragma unroll
;                 for (int i = 0; i < 8; ++i) {
;                     asm volatile("" ::: "memory");
;                     const f32x4 xx = prev[i] - cur[i];
; #pragma unroll
;                     for (int k = 0; k < 6; ++k) {
;                         const f32x4 m4 = ((const f32x4*)(mu + (size_t)k * DM))[i * 64 + lane];
;                         const f32x4 o4 = cur[i] + xx * m4;
;                         h16x4 o = {(h16)o4[0], (h16)o4[1], (h16)o4[2], (h16)o4[3]};
;                         ((h16x4*)(mix + ((size_t)k * MTOK + row) * DM))[i * 64 + lane] = o;
;                     }
;                     prev[i] = cur[i];
;                 }
	v_pk_fma_f32 v[50:51], v[58:59], v[50:51], v[30:31]
	v_pk_fma_f32 v[48:49], v[56:57], v[48:49], v[28:29]
	s_nop 0
	v_cvt_pk_f16_f32 v48, v48, v49
	v_cvt_pk_f16_f32 v49, v50, v51
	global_store_dwordx2 v[166:167], v[48:49], off offset:2048
	ds_read_b128 v[48:51], v230 offset:28672
	s_waitcnt lgkmcnt(0)
	v_pk_fma_f32 v[50:51], v[58:59], v[50:51], v[30:31]
	v_pk_fma_f32 v[48:49], v[56:57], v[48:49], v[28:29]
	s_nop 0
	v_cvt_pk_f16_f32 v48, v48, v49
	v_cvt_pk_f16_f32 v49, v50, v51
	global_store_dwordx2 v[168:169], v[48:49], off offset:2048
	ds_read_b128 v[48:51], v230 offset:36864
	s_waitcnt lgkmcnt(0)
	v_pk_fma_f32 v[50:51], v[58:59], v[50:51], v[30:31]
	v_pk_fma_f32 v[48:49], v[56:57], v[48:49], v[28:29]
	s_nop 0
	v_cvt_pk_f16_f32 v48, v48, v49
	v_cvt_pk_f16_f32 v49, v50, v51
	global_store_dwordx2 v[172:173], v[48:49], off offset:2048
	ds_read_b128 v[48:51], v230 offset:45056
	s_waitcnt lgkmcnt(0)
	v_pk_fma_f32 v[50:51], v[58:59], v[50:51], v[30:31]
	v_pk_fma_f32 v[48:49], v[56:57], v[48:49], v[28:29]
	v_mov_b64_e32 v[58:59], v[18:19]
	v_cvt_pk_f16_f32 v48, v48, v49
	v_cvt_pk_f16_f32 v49, v50, v51
	global_store_dwordx2 v[170:171], v[48:49], off offset:2048
	ds_read_b128 v[48:51], v230 offset:5120
	v_mov_b64_e32 v[56:57], v[16:17]
	s_waitcnt lgkmcnt(0)
	v_pk_fma_f32 v[44:45], v[54:55], v[50:51], v[34:35]
	v_pk_fma_f32 v[46:47], v[52:53], v[48:49], v[32:33]
	v_sub_f32_e32 v49, v41, v37
	v_cvt_pk_f16_f32 v46, v46, v47
	v_cvt_pk_f16_f32 v47, v44, v45
	global_store_dwordx2 v[64:65], v[46:47], off offset:2560
	ds_read_b128 v[44:47], v230 offset:13312
	v_sub_f32_e32 v48, v40, v36
	v_sub_f32_e32 v51, v43, v39
	v_sub_f32_e32 v50, v42, v38
	s_waitcnt lgkmcnt(0)
	v_pk_fma_f32 v[46:47], v[54:55], v[46:47], v[34:35]
	v_pk_fma_f32 v[44:45], v[52:53], v[44:45], v[32:33]
	s_nop 0
	v_cvt_pk_f16_f32 v44, v44, v45
	v_cvt_pk_f16_f32 v45, v46, v47
	global_store_dwordx2 v[66:67], v[44:45], off offset:2560
	ds_read_b128 v[44:47], v230 offset:21504
	s_waitcnt lgkmcnt(0)
	v_pk_fma_f32 v[46:47], v[54:55], v[46:47], v[34:35]
	v_pk_fma_f32 v[44:45], v[52:53], v[44:45], v[32:33]
	s_nop 0
	v_cvt_pk_f16_f32 v44, v44, v45
	v_cvt_pk_f16_f32 v45, v46, v47
	global_store_dwordx2 v[166:167], v[44:45], off offset:2560
	ds_read_b128 v[44:47], v230 offset:29696
	s_waitcnt lgkmcnt(0)
	v_pk_fma_f32 v[46:47], v[54:55], v[46:47], v[34:35]
	v_pk_fma_f32 v[44:45], v[52:53], v[44:45], v[32:33]
	s_nop 0
	v_cvt_pk_f16_f32 v44, v44, v45
	v_cvt_pk_f16_f32 v45, v46, v47
	global_store_dwordx2 v[168:169], v[44:45], off offset:2560
	ds_read_b128 v[44:47], v230 offset:37888
	s_waitcnt lgkmcnt(0)
	v_pk_fma_f32 v[46:47], v[54:55], v[46:47], v[34:35]
	v_pk_fma_f32 v[44:45], v[52:53], v[44:45], v[32:33]
	s_nop 0
	v_cvt_pk_f16_f32 v44, v44, v45
	v_cvt_pk_f16_f32 v45, v46, v47
	global_store_dwordx2 v[172:173], v[44:45], off offset:2560
	ds_read_b128 v[44:47], v230 offset:46080
	s_waitcnt lgkmcnt(0)
	v_pk_fma_f32 v[46:47], v[54:55], v[46:47], v[34:35]
	v_pk_fma_f32 v[44:45], v[52:53], v[44:45], v[32:33]
	v_mov_b64_e32 v[54:55], v[26:27]
	v_cvt_pk_f16_f32 v44, v44, v45
	v_cvt_pk_f16_f32 v45, v46, v47
	global_store_dwordx2 v[170:171], v[44:45], off offset:2560
	ds_read_b128 v[44:47], v230 offset:6144
	v_mov_b64_e32 v[52:53], v[24:25]
	s_waitcnt lgkmcnt(0)
	v_pk_fma_f32 v[40:41], v[50:51], v[46:47], v[38:39]
	v_pk_fma_f32 v[42:43], v[48:49], v[44:45], v[36:37]
	v_mov_b64_e32 v[46:47], v[34:35]
	v_cvt_pk_f16_f32 v42, v42, v43
	v_cvt_pk_f16_f32 v43, v40, v41
	global_store_dwordx2 v[64:65], v[42:43], off offset:3072
	ds_read_b128 v[40:43], v230 offset:14336
	v_mov_b64_e32 v[44:45], v[32:33]
	s_waitcnt lgkmcnt(0)
; template <bool LN>
; __device__ __forceinline__ void ln_phase(const void* src, const float* g, const float* bt, float* xout, h16* xh, const float* mu, h16* mix) {
;     ...
;             if (mix) {
; #pragma unroll
;                 for (int i = 0; i < 8; ++i) {
;                     asm volatile("" ::: "memory");
;                     const f32x4 xx = prev[i] - cur[i];
; #pragma unroll
;                     for (int k = 0; k < 6; ++k) {
;                         const f32x4 m4 = ((const f32x4*)(mu + (size_t)k * DM))[i * 64 + lane];
;                         const f32x4 o4 = cur[i] + xx * m4;
;                         h16x4 o = {(h16)o4[0], (h16)o4[1], (h16)o4[2], (h16)o4[3]};
;                         ((h16x4*)(mix + ((size_t)k * MTOK + row) * DM))[i * 64 + lane] = o;
;                     }
;                     prev[i] = cur[i];
;                 }
	v_pk_fma_f32 v[42:43], v[50:51], v[42:43], v[38:39]
	v_pk_fma_f32 v[40:41], v[48:49], v[40:41], v[36:37]
	s_nop 0
	v_cvt_pk_f16_f32 v40, v40, v41
	v_cvt_pk_f16_f32 v41, v42, v43
	global_store_dwordx2 v[66:67], v[40:41], off offset:3072
	ds_read_b128 v[40:43], v230 offset:22528
	s_waitcnt lgkmcnt(0)
	v_pk_fma_f32 v[42:43], v[50:51], v[42:43], v[38:39]
	v_pk_fma_f32 v[40:41], v[48:49], v[40:41], v[36:37]
	s_nop 0
	v_cvt_pk_f16_f32 v40, v40, v41
	v_cvt_pk_f16_f32 v41, v42, v43
	global_store_dwordx2 v[166:167], v[40:41], off offset:3072
	ds_read_b128 v[40:43], v230 offset:30720
	s_waitcnt lgkmcnt(0)
	v_pk_fma_f32 v[42:43], v[50:51], v[42:43], v[38:39]
	v_pk_fma_f32 v[40:41], v[48:49], v[40:41], v[36:37]
	s_nop 0
	v_cvt_pk_f16_f32 v40, v40, v41
	v_cvt_pk_f16_f32 v41, v42, v43
	global_store_dwordx2 v[168:169], v[40:41], off offset:3072
	ds_read_b128 v[40:43], v230 offset:38912
	s_waitcnt lgkmcnt(0)
	v_pk_fma_f32 v[42:43], v[50:51], v[42:43], v[38:39]
	v_pk_fma_f32 v[40:41], v[48:49], v[40:41], v[36:37]
	s_nop 0
	v_cvt_pk_f16_f32 v40, v40, v41
	v_cvt_pk_f16_f32 v41, v42, v43
	global_store_dwordx2 v[172:173], v[40:41], off offset:3072
	ds_read_b128 v[40:43], v230 offset:47104
	s_waitcnt lgkmcnt(0)
	v_pk_fma_f32 v[42:43], v[50:51], v[42:43], v[38:39]
	v_pk_fma_f32 v[40:41], v[48:49], v[40:41], v[36:37]
	v_mov_b64_e32 v[50:51], v[30:31]
	v_cvt_pk_f16_f32 v40, v40, v41
	v_cvt_pk_f16_f32 v41, v42, v43
	global_store_dwordx2 v[170:171], v[40:41], off offset:3072
	ds_read_b128 v[40:43], v230 offset:7168
	v_mov_b64_e32 v[48:49], v[28:29]
	s_waitcnt lgkmcnt(0)
	v_pk_fma_f32 v[4:5], v[176:177], v[42:43], v[22:23]
	v_pk_fma_f32 v[6:7], v[174:175], v[40:41], v[20:21]
	v_mov_b64_e32 v[42:43], v[38:39]
	v_cvt_pk_f16_f32 v6, v6, v7
	v_cvt_pk_f16_f32 v7, v4, v5
	global_store_dwordx2 v[64:65], v[6:7], off offset:3584
	ds_read_b128 v[4:7], v230 offset:15360
	v_mov_b64_e32 v[40:41], v[36:37]
	s_waitcnt lgkmcnt(0)
	v_pk_fma_f32 v[6:7], v[176:177], v[6:7], v[22:23]
	v_pk_fma_f32 v[4:5], v[174:175], v[4:5], v[20:21]
	s_nop 0
	v_cvt_pk_f16_f32 v4, v4, v5
	v_cvt_pk_f16_f32 v5, v6, v7
	global_store_dwordx2 v[66:67], v[4:5], off offset:3584
	ds_read_b128 v[4:7], v230 offset:23552
	v_mov_b64_e32 v[66:67], v[10:11]
	v_mov_b64_e32 v[64:65], v[8:9]
	s_waitcnt lgkmcnt(0)
	v_pk_fma_f32 v[6:7], v[176:177], v[6:7], v[22:23]
	v_pk_fma_f32 v[4:5], v[174:175], v[4:5], v[20:21]
	s_nop 0
	v_cvt_pk_f16_f32 v4, v4, v5
	v_cvt_pk_f16_f32 v5, v6, v7
	global_store_dwordx2 v[166:167], v[4:5], off offset:3584
	ds_read_b128 v[4:7], v230 offset:31744
	s_waitcnt lgkmcnt(0)
	v_pk_fma_f32 v[6:7], v[176:177], v[6:7], v[22:23]
	v_pk_fma_f32 v[4:5], v[174:175], v[4:5], v[20:21]
	s_nop 0
	v_cvt_pk_f16_f32 v4, v4, v5
	v_cvt_pk_f16_f32 v5, v6, v7
	global_store_dwordx2 v[168:169], v[4:5], off offset:3584
	ds_read_b128 v[4:7], v230 offset:39936
	s_waitcnt lgkmcnt(0)
	v_pk_fma_f32 v[6:7], v[176:177], v[6:7], v[22:23]
	v_pk_fma_f32 v[4:5], v[174:175], v[4:5], v[20:21]
	s_nop 0
	v_cvt_pk_f16_f32 v4, v4, v5
	v_cvt_pk_f16_f32 v5, v6, v7
	global_store_dwordx2 v[172:173], v[4:5], off offset:3584
	ds_read_b128 v[166:169], v230 offset:48128
	v_mov_b64_e32 v[4:5], v[20:21]
	v_mov_b64_e32 v[6:7], v[22:23]
	s_waitcnt lgkmcnt(0)
	v_pk_fma_f32 v[8:9], v[176:177], v[168:169], v[22:23]
	v_pk_fma_f32 v[10:11], v[174:175], v[166:167], v[20:21]
	s_nop 0
	v_cvt_pk_f16_f32 v10, v10, v11
	v_cvt_pk_f16_f32 v11, v8, v9
	global_store_dwordx2 v[170:171], v[10:11], off offset:3584
	s_cbranch_scc0 .LBB0_1013
	v_readlane_b32 s4, v254, 1
	v_readlane_b32 s5, v254, 2
	v_add_u32_e32 v68, s48, v68
	v_cmp_lt_i32_e32 vcc, s2, v68
	v_lshl_add_u64 v[116:117], v[116:117], 0, s[4:5]
	v_readlane_b32 s4, v254, 3
	v_readlane_b32 s5, v254, 4
	s_or_b64 s[22:23], vcc, s[22:23]
	s_nop 0
	v_lshl_add_u64 v[118:119], v[118:119], 0, s[4:5]
	s_andn2_b64 exec, exec, s[22:23]
	s_cbranch_execnz .LBB0_1010
